# V-transpose loops: both row loads issued before a counted wait; phase_up: conv weight/bias loads issued right after the k-loop instead of after the staging barrier
# speedup vs baseline: 1.0066x; 1.0001x over previous
; #define WAIT_V0() asm volatile("s_waitcnt vmcnt(0)" ::: "memory")
; DI int glds_row(int i) { const int tid = ltid(); return ((tid >> 6) * 4 + i) * 8 + ((tid & 63) >> 3); }
; DI int glds_chunk(int row) { return (ltid() & 7) ^ ((row >> 1) & 7); }
; DI void gemm_core(char* smem, int nk, const char* Ab, const char* Bb, const unsigned (&aoff)[4], const unsigned (&boff)[4],
;                   f32x16 (&acc)[2][2]) {
;     ...
;   auto stage = [&](int buf, int kt) __attribute__((always_inline)) {
;     const char* ak = Ab + kt * 128;
;     const char* bk = Bb + kt * 128;
;     char* sa = smem + buf * STAGE_B + w * 4096;
; #pragma unroll
;     for (int i = 0; i < 4; ++i) {
;       __builtin_amdgcn_global_load_lds((const unsigned*)(ak + aoff[i]), (unsigned*)(sa + i * 1024), 16, 0, 0);
;       __builtin_amdgcn_global_load_lds((const unsigned*)(bk + boff[i]), (unsigned*)(sa + 16384 + i * 1024), 16, 0, 0);
;     }
;   };
;   stage(0, 0);
;   WAIT_V0();
;   __syncthreads();
; DI void phase_up(const Params& P, int layer, char* smem) {
;     ...
;   for (int t0 = blockIdx.x; t0 < MT * NT; t0 += gridDim.x) {
;     const int tl = xcd_tile(t0, MT * NT) - (t0 & 7) * ((MT * NT) >> 3);
;     const int mt = (t0 & 1) * 131 + tl / 11, nt = ((t0 & 7) >> 1) * 11 + tl % 11;
;     const int b = mt / 131, i = mt % 131;
;     const int tb0 = i * 126 - 2;
;     unsigned aoff[4], boff[4];
;     const char* Abase = (const char*)(hn + (size_t)b * S_ * 1024);
;     const unsigned zoff = (unsigned)((P.ws + OFF_ZPAGE) - Abase);
; #pragma unroll
;     for (int q = 0; q < 4; ++q) {
;       const int r = glds_row(q), ch = glds_chunk(r);
;       const int tb = tb0 + r;
;       const bool ok = (tb >= 0) && (tb < S_);
;       aoff[q] = ok ? (unsigned)((tb * 1024 + ch * 8) * 2) : zoff;
;       const int wr = (r < 64) ? (nt * 64 + r) : (DFF + nt * 64 + r - 64);
;       boff[q] = (unsigned)((wr * 1024 + ch * 8) * 2);
;     }
;     f32x16 acc[2][2];
;     gemm_core(smem, 16, Abase, (const char*)wup, aoff, boff, acc);
.LBB0_25:
	s_ashr_i32 s18, s2, 3
	s_and_b32 s19, s18, 0xffffffc0
	s_lshl_b32 s20, s18, 1
	s_bfe_u32 s21, s18, 0x10005
	s_and_b32 s20, s20, 62
	s_or_b32 s19, s21, s19
	s_or_b32 s19, s19, s20
	s_or_b32 s20, s18, 63
	s_cmpk_lt_i32 s20, 0x5a1
	s_cselect_b32 s18, s19, s18
	s_bitcmp1_b32 s2, 0
	s_mul_hi_i32 s20, s18, 0x2e8ba2e9
	s_cselect_b32 s19, 0x83, 0
	s_lshr_b32 s21, s20, 31
	s_ashr_i32 s20, s20, 1
	s_add_i32 s21, s20, s21
	s_add_i32 s20, s21, s19
	s_bfe_u32 s19, s2, 0x20001
	s_mul_i32 s21, s21, 11
	s_mul_i32 s19, s19, 11
	s_sub_i32 s18, s18, s21
	s_add_i32 s21, s18, s19
	s_mul_hi_i32 s18, s20, 0x3e88cb3d
	s_lshr_b32 s19, s18, 31
	s_ashr_i32 s18, s18, 5
	v_mov_b32_e32 v0, v161
	s_add_i32 s68, s18, s19
	s_mul_i32 s18, s68, 0x83
	v_ashrrev_i32_e32 v1, 1, v0
	v_lshrrev_b32_e32 v2, 3, v0
	v_bfe_u32 v0, v0, 3, 3
	s_movk_i32 s3, 0xffe0
	s_sub_i32 s28, s20, s18
	v_and_or_b32 v0, v1, s3, v0
	v_mov_b32_e32 v1, v161
	s_mulk_i32 s28, 0x7e
	s_ashr_i32 s69, s68, 31
	v_bfe_u32 v2, v2, 1, 2
	s_add_i32 s29, s28, -2
	s_lshl_b64 s[22:23], s[68:69], 25
	v_xor_b32_e32 v1, v2, v1
	s_add_u32 s18, s84, s22
	v_lshlrev_b32_e32 v1, 4, v1
	s_addc_u32 s19, s85, s23
	s_sub_i32 s22, 0x1b508000, s22
	s_lshl_b32 s21, s21, 6
	v_add_u32_e32 v2, s29, v0
	v_and_b32_e32 v1, 0x70, v1
	s_movk_i32 s3, 0x4000
	s_add_i32 s23, s21, 0xac0
	v_lshl_or_b32 v3, v2, 11, v1
	v_mov_b32_e32 v4, s22
	v_cmp_gt_u32_e32 vcc, s3, v2
	v_mov_b32_e32 v5, s21
	v_mov_b32_e32 v12, v161
	v_cndmask_b32_e32 v136, v4, v3, vcc
	v_mov_b32_e32 v3, s23
	v_cmp_gt_i32_e32 vcc, 64, v0
	v_lshl_add_u64 v[64:65], s[18:19], 0, v[136:137]
	s_mov_b64 s[4:5], 0x100
	v_cndmask_b32_e32 v2, v3, v5, vcc
	v_add_u32_e32 v0, v2, v0
	v_lshl_or_b32 v76, v0, 11, v1
	v_mov_b32_e32 v0, v161
	s_mov_b64 s[6:7], 0x780
	v_ashrrev_i32_e32 v1, 1, v0
	v_and_b32_e32 v1, 0xffffffe0, v1
	v_bfe_u32 v0, v0, 3, 3
	v_or3_b32 v1, v1, v0, 8
	v_mov_b32_e32 v0, v161
	v_lshrrev_b32_e32 v2, 1, v1
	v_xor_b32_e32 v0, v2, v0
	v_lshlrev_b32_e32 v0, 4, v0
	v_add_u32_e32 v2, s29, v1
	v_and_b32_e32 v6, 0x70, v0
	v_lshl_or_b32 v0, v2, 11, v6
	v_cmp_gt_u32_e32 vcc, s3, v2
	s_nop 1
	v_cndmask_b32_e32 v0, v4, v0, vcc
	v_cmp_gt_i32_e32 vcc, 64, v1
	s_nop 1
	v_cndmask_b32_e32 v2, v3, v5, vcc
	v_add_u32_e32 v1, v2, v1
	v_lshl_or_b32 v77, v1, 11, v6
	v_mov_b32_e32 v1, v161
	s_nop 0
	v_ashrrev_i32_e32 v2, 1, v1
	v_and_b32_e32 v2, 0xffffffe0, v2
	v_lshrrev_b32_e32 v6, 3, v1
	v_bfe_u32 v1, v1, 3, 3
	v_or3_b32 v1, v2, v1, 16
	v_mov_b32_e32 v2, v161
	v_bfe_u32 v6, v6, 1, 2
	v_xor_b32_e32 v2, v6, v2
	v_lshlrev_b32_e32 v2, 4, v2
	v_add_u32_e32 v6, s29, v1
	v_and_b32_e32 v7, 0x70, v2
	v_lshl_or_b32 v2, v6, 11, v7
	v_cmp_gt_u32_e32 vcc, s3, v6
	s_nop 1
	v_cndmask_b32_e32 v2, v4, v2, vcc
	v_cmp_gt_i32_e32 vcc, 64, v1
	s_nop 1
	v_cndmask_b32_e32 v6, v3, v5, vcc
	v_add_u32_e32 v1, v6, v1
	v_lshl_or_b32 v78, v1, 11, v7
	v_mov_b32_e32 v1, v161
	s_nop 0
	v_ashrrev_i32_e32 v6, 1, v1
	v_and_b32_e32 v6, 0xffffffe0, v6
	v_bfe_u32 v1, v1, 3, 3
	v_or3_b32 v1, v6, v1, 24
	v_mov_b32_e32 v6, v161
	v_lshrrev_b32_e32 v7, 1, v1
	v_xor_b32_e32 v6, v7, v6
	v_lshlrev_b32_e32 v6, 4, v6
	v_add_u32_e32 v7, s29, v1
	v_and_b32_e32 v6, 0x70, v6
	v_lshl_or_b32 v8, v7, 11, v6
	v_cmp_gt_u32_e32 vcc, s3, v7
	s_mov_b32 s3, 0x1ffffc0
	v_bfe_u32 v86, v12, 1, 3
	v_cndmask_b32_e32 v4, v4, v8, vcc
	v_cmp_gt_i32_e32 vcc, 64, v1
	v_bfe_u32 v117, v12, 5, 1
	s_nop 0
	v_cndmask_b32_e32 v3, v3, v5, vcc
	v_add_u32_e32 v1, v3, v1
	v_lshl_or_b32 v84, v1, 11, v6
	v_and_b32_e32 v1, 31, v12
	v_lshrrev_b32_e32 v5, 1, v12
	v_and_or_b32 v1, v5, s3, v1
	v_lshlrev_b32_e32 v87, 7, v1
	v_lshlrev_b32_e32 v1, 6, v12
	v_and_b32_e32 v97, 0xfffff000, v1
	v_add_u32_e32 v96, 0x4000, v97
	v_readfirstlane_b32 s84, v97
	s_mov_b32 m0, s84
	v_readfirstlane_b32 s85, v96
	v_or_b32_e32 v98, 0x400, v97
	global_load_lds_dwordx4 v136, s[18:19]
	s_mov_b32 m0, s85
	v_readfirstlane_b32 s86, v98
	v_add_u32_e32 v99, 0x4400, v97
	global_load_lds_dwordx4 v76, s[0:1]
	s_mov_b32 m0, s86
	v_readfirstlane_b32 s87, v99
	v_or_b32_e32 v100, 0x800, v97
	global_load_lds_dwordx4 v0, s[18:19]
	s_mov_b32 m0, s87
	v_readfirstlane_b32 s88, v100
	v_add_u32_e32 v101, 0x4800, v97
	v_lshrrev_b32_e32 v3, 5, v12
	global_load_lds_dwordx4 v77, s[0:1]
	s_mov_b32 m0, s88
	v_readfirstlane_b32 s89, v101
	v_or_b32_e32 v102, 0xc00, v97
	v_bitop3_b32 v3, v3, v86, 1 bitop3:0x6c
	global_load_lds_dwordx4 v2, s[18:19]
	s_mov_b32 m0, s89
	v_readfirstlane_b32 s90, v102
	v_add_u32_e32 v103, 0x4c00, v97
	v_lshlrev_b32_e32 v6, 4, v3
	v_mov_b32_e32 v1, v137
	v_mov_b32_e32 v3, v137
	global_load_lds_dwordx4 v78, s[0:1]
	v_mov_b32_e32 v5, v137
	s_mov_b32 m0, s90
	v_readfirstlane_b32 s91, v103
	v_add_u32_e32 v89, 0x8000, v97
	v_lshl_add_u64 v[66:67], s[18:19], 0, v[0:1]
	v_lshl_add_u64 v[68:69], s[18:19], 0, v[2:3]
	v_lshl_add_u64 v[70:71], s[18:19], 0, v[4:5]
	global_load_lds_dwordx4 v4, s[18:19]
	s_mov_b32 m0, s91
	v_add_u32_e32 v88, 0xc000, v97
	v_readfirstlane_b32 s18, v89
	global_load_lds_dwordx4 v84, s[0:1]
	v_lshl_add_u64 v[0:1], v[64:65], 0, s[94:95]
	s_mov_b32 m0, s18
	v_readfirstlane_b32 s19, v88
	v_add_u32_e32 v90, 0x8400, v97
	s_waitcnt vmcnt(0)
	s_waitcnt vmcnt(0) lgkmcnt(0)
	s_barrier
; #define WAIT_V0() asm volatile("s_waitcnt vmcnt(0)" ::: "memory")
; DI void gemm_core(char* smem, int nk, const char* Ab, const char* Bb, const unsigned (&aoff)[4], const unsigned (&boff)[4],
;                   f32x16 (&acc)[2][2]) {
;     ...
;   for (int kt = 0; kt < nk; ++kt) {
;     const int cur = kt & 1;
;     if (kt + 1 < nk) stage(cur ^ 1, kt + 1);
;     const char* sb = smem + cur * STAGE_B;
; #pragma unroll
;     for (int ks = 0; ks < 4; ++ks) {
;       bf16x8 af[2], bfr[2];
; #pragma unroll
;       for (int mb = 0; mb < 2; ++mb) af[mb] = *(const bf16x8*)(sb + a_base + mb * 4096 + xo[ks]);
; #pragma unroll
;       for (int nb = 0; nb < 2; ++nb) bfr[nb] = *(const bf16x8*)(sb + b_base + nb * 4096 + xo[ks]);
; #pragma unroll
;       for (int mb = 0; mb < 2; ++mb)
; #pragma unroll
;         for (int nb = 0; nb < 2; ++nb)
;           acc[mb][nb] = __builtin_amdgcn_mfma_f32_32x32x16_bf16(af[mb], bfr[nb], acc[mb][nb], 0, 0, 0);
;     }
;     WAIT_V0();
;     __syncthreads();
;   }
	global_load_lds_dwordx4 v[0:1], off
	s_mov_b32 m0, s19
	v_readfirstlane_b32 s22, v90
	v_add_u32_e32 v91, 0xc400, v97
	global_load_lds_dwordx4 v76, s[14:15]
	v_lshl_add_u64 v[0:1], v[66:67], 0, s[94:95]
	s_mov_b32 m0, s22
	v_readfirstlane_b32 s23, v91
	v_add_u32_e32 v92, 0x8800, v97
	global_load_lds_dwordx4 v[0:1], off
	s_mov_b32 m0, s23
	v_readfirstlane_b32 s29, v92
	v_add_u32_e32 v93, 0xc800, v97
	global_load_lds_dwordx4 v77, s[14:15]
	v_lshl_add_u64 v[0:1], v[68:69], 0, s[94:95]
	s_mov_b32 m0, s29
	v_readfirstlane_b32 s69, v93
	v_add_u32_e32 v94, 0x8c00, v97
	global_load_lds_dwordx4 v[0:1], off
	s_mov_b32 m0, s69
	v_readfirstlane_b32 s70, v94
	v_add_u32_e32 v95, 0xcc00, v97
	global_load_lds_dwordx4 v78, s[14:15]
	v_lshl_add_u64 v[0:1], v[70:71], 0, s[94:95]
	s_mov_b32 m0, s70
	v_readfirstlane_b32 s71, v95
	global_load_lds_dwordx4 v[0:1], off
	s_mov_b32 m0, s71
	v_or_b32_e32 v79, v87, v6
	global_load_lds_dwordx4 v84, s[14:15]
	ds_read_b128 v[0:3], v79
	v_lshlrev_b32_e32 v4, 7, v12
	v_and_b32_e32 v116, 0x2f80, v4
	v_or_b32_e32 v81, v116, v6
	ds_read_b128 v[4:7], v81 offset:16384
	ds_read_b128 v[8:11], v81 offset:20480
	s_waitcnt lgkmcnt(0)
	v_mfma_f32_32x32x16_bf16 v[48:63], v[0:3], v[4:7], 0
	s_mov_b32 m0, s84
	s_mov_b32 s3, 0xfffffc0
	v_mfma_f32_32x32x16_bf16 v[32:47], v[0:3], v[8:11], 0
	ds_read_b128 v[0:3], v79 offset:4096
	s_waitcnt lgkmcnt(0)
	v_mfma_f32_32x32x16_bf16 v[16:31], v[0:3], v[4:7], 0
	v_bitop3_b32 v4, v117, v86, 2 bitop3:0x36
	v_lshlrev_b32_e32 v82, 4, v4
	v_or_b32_e32 v80, v87, v82
	ds_read_b128 v[104:107], v80
	v_or_b32_e32 v83, v116, v82
	ds_read_b128 v[108:111], v83 offset:16384
	ds_read_b128 v[112:115], v83 offset:20480
	s_waitcnt lgkmcnt(0)
	v_mfma_f32_32x32x16_bf16 v[48:63], v[104:107], v[108:111], v[48:63]
	v_bitop3_b32 v82, v117, v86, 4 bitop3:0x36
	v_lshlrev_b32_e32 v85, 4, v82
	v_or_b32_e32 v82, v87, v85
	v_or_b32_e32 v85, v116, v85
	v_bitop3_b32 v86, v117, v86, 6 bitop3:0x36
	v_mfma_f32_32x32x16_bf16 v[32:47], v[104:107], v[112:115], v[32:47]
	ds_read_b128 v[104:107], v80 offset:4096
	v_mfma_f32_32x32x16_bf16 v[0:15], v[0:3], v[8:11], 0
	s_waitcnt lgkmcnt(0)
	v_mfma_f32_32x32x16_bf16 v[16:31], v[104:107], v[108:111], v[16:31]
	ds_read_b128 v[108:111], v85 offset:16384
	v_mfma_f32_32x32x16_bf16 v[0:15], v[104:107], v[112:115], v[0:15]
	ds_read_b128 v[104:107], v82
	ds_read_b128 v[112:115], v85 offset:20480
	s_waitcnt lgkmcnt(0)
	v_mfma_f32_32x32x16_bf16 v[48:63], v[104:107], v[108:111], v[48:63]
	v_mfma_f32_32x32x16_bf16 v[32:47], v[104:107], v[112:115], v[32:47]
	ds_read_b128 v[104:107], v82 offset:4096
	s_waitcnt lgkmcnt(0)
	v_mfma_f32_32x32x16_bf16 v[16:31], v[104:107], v[108:111], v[16:31]
	v_lshlrev_b32_e32 v108, 4, v86
	v_or_b32_e32 v86, v87, v108
	v_or_b32_e32 v87, v116, v108
	ds_read_b128 v[108:111], v87 offset:16384
	v_mfma_f32_32x32x16_bf16 v[0:15], v[104:107], v[112:115], v[0:15]
	ds_read_b128 v[104:107], v86
	ds_read_b128 v[112:115], v87 offset:20480
	s_waitcnt lgkmcnt(0)
	v_mfma_f32_32x32x16_bf16 v[48:63], v[104:107], v[108:111], v[48:63]
	v_mfma_f32_32x32x16_bf16 v[32:47], v[104:107], v[112:115], v[32:47]
	ds_read_b128 v[104:107], v86 offset:4096
	s_waitcnt vmcnt(0)
	s_waitcnt vmcnt(0) lgkmcnt(0)
	s_barrier
	v_mfma_f32_32x32x16_bf16 v[16:31], v[104:107], v[108:111], v[16:31]
	v_mfma_f32_32x32x16_bf16 v[0:15], v[104:107], v[112:115], v[0:15]
	v_lshl_add_u64 v[104:105], v[64:65], 0, s[4:5]
	global_load_lds_dwordx4 v[104:105], off
	s_mov_b32 m0, s85
	v_lshl_add_u64 v[104:105], v[66:67], 0, s[4:5]
	global_load_lds_dwordx4 v76, s[16:17]
	s_mov_b32 m0, s86
	s_nop 0
	global_load_lds_dwordx4 v[104:105], off
	s_mov_b32 m0, s87
	v_lshl_add_u64 v[104:105], v[68:69], 0, s[4:5]
	global_load_lds_dwordx4 v77, s[16:17]
	s_mov_b32 m0, s88
	s_nop 0
	global_load_lds_dwordx4 v[104:105], off
	s_mov_b32 m0, s89
	v_lshl_add_u64 v[104:105], v[70:71], 0, s[4:5]
	global_load_lds_dwordx4 v78, s[16:17]
	s_mov_b32 m0, s90
	s_mov_b64 s[4:5], 0x180
	global_load_lds_dwordx4 v[104:105], off
	s_mov_b32 m0, s91
	s_nop 0
	global_load_lds_dwordx4 v84, s[16:17]
	ds_read_b128 v[104:107], v79 offset:32768
	ds_read_b128 v[108:111], v81 offset:49152
	ds_read_b128 v[112:115], v81 offset:53248
	s_waitcnt lgkmcnt(0)
	v_mfma_f32_32x32x16_bf16 v[48:63], v[104:107], v[108:111], v[48:63]
	s_mov_b32 m0, s18
	v_mfma_f32_32x32x16_bf16 v[32:47], v[104:107], v[112:115], v[32:47]
	ds_read_b128 v[104:107], v79 offset:36864
	s_waitcnt lgkmcnt(0)
	v_mfma_f32_32x32x16_bf16 v[16:31], v[104:107], v[108:111], v[16:31]
	v_mfma_f32_32x32x16_bf16 v[0:15], v[104:107], v[112:115], v[0:15]
	ds_read_b128 v[104:107], v80 offset:32768
	ds_read_b128 v[108:111], v83 offset:49152
	ds_read_b128 v[112:115], v83 offset:53248
	s_waitcnt lgkmcnt(0)
	v_mfma_f32_32x32x16_bf16 v[48:63], v[104:107], v[108:111], v[48:63]
	v_mfma_f32_32x32x16_bf16 v[32:47], v[104:107], v[112:115], v[32:47]
	ds_read_b128 v[104:107], v80 offset:36864
	s_waitcnt lgkmcnt(0)
	v_mfma_f32_32x32x16_bf16 v[16:31], v[104:107], v[108:111], v[16:31]
	v_mfma_f32_32x32x16_bf16 v[0:15], v[104:107], v[112:115], v[0:15]
	ds_read_b128 v[104:107], v82 offset:32768
	ds_read_b128 v[108:111], v85 offset:49152
	ds_read_b128 v[112:115], v85 offset:53248
	s_waitcnt lgkmcnt(0)
	v_mfma_f32_32x32x16_bf16 v[48:63], v[104:107], v[108:111], v[48:63]
	v_mfma_f32_32x32x16_bf16 v[32:47], v[104:107], v[112:115], v[32:47]
	ds_read_b128 v[104:107], v82 offset:36864
	s_waitcnt lgkmcnt(0)
	v_mfma_f32_32x32x16_bf16 v[16:31], v[104:107], v[108:111], v[16:31]
	v_mfma_f32_32x32x16_bf16 v[0:15], v[104:107], v[112:115], v[0:15]
	ds_read_b128 v[104:107], v86 offset:32768
	ds_read_b128 v[108:111], v87 offset:49152
	ds_read_b128 v[112:115], v87 offset:53248
	s_waitcnt lgkmcnt(0)
	v_mfma_f32_32x32x16_bf16 v[48:63], v[104:107], v[108:111], v[48:63]
	v_mfma_f32_32x32x16_bf16 v[32:47], v[104:107], v[112:115], v[32:47]
	ds_read_b128 v[104:107], v86 offset:36864
	s_waitcnt vmcnt(0)
	s_waitcnt vmcnt(0) lgkmcnt(0)
	s_barrier
; #define WAIT_V0() asm volatile("s_waitcnt vmcnt(0)" ::: "memory")
; DI void gemm_core(char* smem, int nk, const char* Ab, const char* Bb, const unsigned (&aoff)[4], const unsigned (&boff)[4],
;                   f32x16 (&acc)[2][2]) {
;     ...
;   for (int kt = 0; kt < nk; ++kt) {
;     const int cur = kt & 1;
;     if (kt + 1 < nk) stage(cur ^ 1, kt + 1);
;     const char* sb = smem + cur * STAGE_B;
; #pragma unroll
;     for (int ks = 0; ks < 4; ++ks) {
;       bf16x8 af[2], bfr[2];
; #pragma unroll
;       for (int mb = 0; mb < 2; ++mb) af[mb] = *(const bf16x8*)(sb + a_base + mb * 4096 + xo[ks]);
; #pragma unroll
;       for (int nb = 0; nb < 2; ++nb) bfr[nb] = *(const bf16x8*)(sb + b_base + nb * 4096 + xo[ks]);
; #pragma unroll
;       for (int mb = 0; mb < 2; ++mb)
; #pragma unroll
;         for (int nb = 0; nb < 2; ++nb)
;           acc[mb][nb] = __builtin_amdgcn_mfma_f32_32x32x16_bf16(af[mb], bfr[nb], acc[mb][nb], 0, 0, 0);
;     }
;     WAIT_V0();
;     __syncthreads();
;   }
	v_mfma_f32_32x32x16_bf16 v[16:31], v[104:107], v[108:111], v[16:31]
	v_mfma_f32_32x32x16_bf16 v[0:15], v[104:107], v[112:115], v[0:15]
	v_lshl_add_u64 v[104:105], v[64:65], 0, s[4:5]
	global_load_lds_dwordx4 v[104:105], off
	s_mov_b32 m0, s19
	v_lshl_add_u64 v[104:105], v[66:67], 0, s[4:5]
	global_load_lds_dwordx4 v76, s[42:43]
	s_mov_b32 m0, s22
	s_nop 0
	global_load_lds_dwordx4 v[104:105], off
	s_mov_b32 m0, s23
	v_lshl_add_u64 v[104:105], v[68:69], 0, s[4:5]
	global_load_lds_dwordx4 v77, s[42:43]
	s_mov_b32 m0, s29
	s_nop 0
	global_load_lds_dwordx4 v[104:105], off
	s_mov_b32 m0, s69
	v_lshl_add_u64 v[104:105], v[70:71], 0, s[4:5]
	global_load_lds_dwordx4 v78, s[42:43]
	s_mov_b32 m0, s70
	s_mov_b64 s[4:5], 0x280
	global_load_lds_dwordx4 v[104:105], off
	s_mov_b32 m0, s71
	s_nop 0
	global_load_lds_dwordx4 v84, s[42:43]
	ds_read_b128 v[104:107], v79
	ds_read_b128 v[108:111], v81 offset:16384
	ds_read_b128 v[112:115], v81 offset:20480
	s_waitcnt lgkmcnt(0)
	v_mfma_f32_32x32x16_bf16 v[48:63], v[104:107], v[108:111], v[48:63]
	s_mov_b32 m0, s84
	v_mfma_f32_32x32x16_bf16 v[32:47], v[104:107], v[112:115], v[32:47]
	ds_read_b128 v[104:107], v79 offset:4096
	s_waitcnt lgkmcnt(0)
	v_mfma_f32_32x32x16_bf16 v[16:31], v[104:107], v[108:111], v[16:31]
	v_mfma_f32_32x32x16_bf16 v[0:15], v[104:107], v[112:115], v[0:15]
	ds_read_b128 v[104:107], v80
	ds_read_b128 v[108:111], v83 offset:16384
	ds_read_b128 v[112:115], v83 offset:20480
	s_waitcnt lgkmcnt(0)
	v_mfma_f32_32x32x16_bf16 v[48:63], v[104:107], v[108:111], v[48:63]
	v_mfma_f32_32x32x16_bf16 v[32:47], v[104:107], v[112:115], v[32:47]
	ds_read_b128 v[104:107], v80 offset:4096
	s_waitcnt lgkmcnt(0)
	v_mfma_f32_32x32x16_bf16 v[16:31], v[104:107], v[108:111], v[16:31]
	v_mfma_f32_32x32x16_bf16 v[0:15], v[104:107], v[112:115], v[0:15]
	ds_read_b128 v[104:107], v82
	ds_read_b128 v[108:111], v85 offset:16384
	ds_read_b128 v[112:115], v85 offset:20480
	s_waitcnt lgkmcnt(0)
	v_mfma_f32_32x32x16_bf16 v[48:63], v[104:107], v[108:111], v[48:63]
	v_mfma_f32_32x32x16_bf16 v[32:47], v[104:107], v[112:115], v[32:47]
	ds_read_b128 v[104:107], v82 offset:4096
	s_waitcnt lgkmcnt(0)
	v_mfma_f32_32x32x16_bf16 v[16:31], v[104:107], v[108:111], v[16:31]
	v_mfma_f32_32x32x16_bf16 v[0:15], v[104:107], v[112:115], v[0:15]
	ds_read_b128 v[104:107], v86
	ds_read_b128 v[108:111], v87 offset:16384
	ds_read_b128 v[112:115], v87 offset:20480
	s_waitcnt lgkmcnt(0)
	v_mfma_f32_32x32x16_bf16 v[48:63], v[104:107], v[108:111], v[48:63]
	v_mfma_f32_32x32x16_bf16 v[32:47], v[104:107], v[112:115], v[32:47]
	ds_read_b128 v[104:107], v86 offset:4096
	s_waitcnt vmcnt(0)
	s_waitcnt vmcnt(0) lgkmcnt(0)
	s_barrier
	v_mfma_f32_32x32x16_bf16 v[16:31], v[104:107], v[108:111], v[16:31]
	v_mfma_f32_32x32x16_bf16 v[0:15], v[104:107], v[112:115], v[0:15]
	v_lshl_add_u64 v[104:105], v[64:65], 0, s[30:31]
	global_load_lds_dwordx4 v[104:105], off
	s_mov_b32 m0, s85
	v_lshl_add_u64 v[104:105], v[66:67], 0, s[30:31]
	global_load_lds_dwordx4 v76, s[44:45]
	s_mov_b32 m0, s86
	s_nop 0
	global_load_lds_dwordx4 v[104:105], off
	s_mov_b32 m0, s87
	v_lshl_add_u64 v[104:105], v[68:69], 0, s[30:31]
	global_load_lds_dwordx4 v77, s[44:45]
	s_mov_b32 m0, s88
	s_nop 0
	global_load_lds_dwordx4 v[104:105], off
	s_mov_b32 m0, s89
	v_lshl_add_u64 v[104:105], v[70:71], 0, s[30:31]
	global_load_lds_dwordx4 v78, s[44:45]
	s_mov_b32 m0, s90
	s_nop 0
	global_load_lds_dwordx4 v[104:105], off
	s_mov_b32 m0, s91
	s_nop 0
	global_load_lds_dwordx4 v84, s[44:45]
	ds_read_b128 v[104:107], v79 offset:32768
	ds_read_b128 v[108:111], v81 offset:49152
	ds_read_b128 v[112:115], v81 offset:53248
	s_waitcnt lgkmcnt(0)
	v_mfma_f32_32x32x16_bf16 v[48:63], v[104:107], v[108:111], v[48:63]
	s_mov_b32 m0, s18
	v_mfma_f32_32x32x16_bf16 v[32:47], v[104:107], v[112:115], v[32:47]
	ds_read_b128 v[104:107], v79 offset:36864
	s_waitcnt lgkmcnt(0)
	v_mfma_f32_32x32x16_bf16 v[16:31], v[104:107], v[108:111], v[16:31]
	v_mfma_f32_32x32x16_bf16 v[0:15], v[104:107], v[112:115], v[0:15]
	ds_read_b128 v[104:107], v80 offset:32768
	ds_read_b128 v[108:111], v83 offset:49152
	ds_read_b128 v[112:115], v83 offset:53248
	s_waitcnt lgkmcnt(0)
	v_mfma_f32_32x32x16_bf16 v[48:63], v[104:107], v[108:111], v[48:63]
	v_mfma_f32_32x32x16_bf16 v[32:47], v[104:107], v[112:115], v[32:47]
	ds_read_b128 v[104:107], v80 offset:36864
	s_waitcnt lgkmcnt(0)
	v_mfma_f32_32x32x16_bf16 v[16:31], v[104:107], v[108:111], v[16:31]
	v_mfma_f32_32x32x16_bf16 v[0:15], v[104:107], v[112:115], v[0:15]
	ds_read_b128 v[104:107], v82 offset:32768
	ds_read_b128 v[108:111], v85 offset:49152
	ds_read_b128 v[112:115], v85 offset:53248
	s_waitcnt lgkmcnt(0)
	v_mfma_f32_32x32x16_bf16 v[48:63], v[104:107], v[108:111], v[48:63]
	v_mfma_f32_32x32x16_bf16 v[32:47], v[104:107], v[112:115], v[32:47]
	ds_read_b128 v[104:107], v82 offset:36864
	s_waitcnt lgkmcnt(0)
	v_mfma_f32_32x32x16_bf16 v[16:31], v[104:107], v[108:111], v[16:31]
	v_mfma_f32_32x32x16_bf16 v[0:15], v[104:107], v[112:115], v[0:15]
	ds_read_b128 v[104:107], v86 offset:32768
	ds_read_b128 v[108:111], v87 offset:49152
	ds_read_b128 v[112:115], v87 offset:53248
	s_waitcnt lgkmcnt(0)
	v_mfma_f32_32x32x16_bf16 v[48:63], v[104:107], v[108:111], v[48:63]
	v_mfma_f32_32x32x16_bf16 v[32:47], v[104:107], v[112:115], v[32:47]
	ds_read_b128 v[104:107], v86 offset:36864
	s_waitcnt vmcnt(0)
	s_waitcnt vmcnt(0) lgkmcnt(0)
	s_barrier
; #define WAIT_V0() asm volatile("s_waitcnt vmcnt(0)" ::: "memory")
; DI void gemm_core(char* smem, int nk, const char* Ab, const char* Bb, const unsigned (&aoff)[4], const unsigned (&boff)[4],
;                   f32x16 (&acc)[2][2]) {
;     ...
;   for (int kt = 0; kt < nk; ++kt) {
;     const int cur = kt & 1;
;     if (kt + 1 < nk) stage(cur ^ 1, kt + 1);
;     const char* sb = smem + cur * STAGE_B;
; #pragma unroll
;     for (int ks = 0; ks < 4; ++ks) {
;       bf16x8 af[2], bfr[2];
; #pragma unroll
;       for (int mb = 0; mb < 2; ++mb) af[mb] = *(const bf16x8*)(sb + a_base + mb * 4096 + xo[ks]);
; #pragma unroll
;       for (int nb = 0; nb < 2; ++nb) bfr[nb] = *(const bf16x8*)(sb + b_base + nb * 4096 + xo[ks]);
; #pragma unroll
;       for (int mb = 0; mb < 2; ++mb)
; #pragma unroll
;         for (int nb = 0; nb < 2; ++nb)
;           acc[mb][nb] = __builtin_amdgcn_mfma_f32_32x32x16_bf16(af[mb], bfr[nb], acc[mb][nb], 0, 0, 0);
;     }
;     WAIT_V0();
;     __syncthreads();
;   }
	v_mfma_f32_32x32x16_bf16 v[16:31], v[104:107], v[108:111], v[16:31]
	v_mfma_f32_32x32x16_bf16 v[0:15], v[104:107], v[112:115], v[0:15]
	v_lshl_add_u64 v[104:105], v[64:65], 0, s[4:5]
	global_load_lds_dwordx4 v[104:105], off
	s_mov_b32 m0, s19
	v_lshl_add_u64 v[104:105], v[66:67], 0, s[4:5]
	global_load_lds_dwordx4 v76, s[46:47]
	s_mov_b32 m0, s22
	s_nop 0
	global_load_lds_dwordx4 v[104:105], off
	s_mov_b32 m0, s23
	v_lshl_add_u64 v[104:105], v[68:69], 0, s[4:5]
	global_load_lds_dwordx4 v77, s[46:47]
	s_mov_b32 m0, s29
	s_nop 0
	global_load_lds_dwordx4 v[104:105], off
	s_mov_b32 m0, s69
	v_lshl_add_u64 v[104:105], v[70:71], 0, s[4:5]
	global_load_lds_dwordx4 v78, s[46:47]
	s_mov_b32 m0, s70
	s_mov_b64 s[4:5], 0x300
	global_load_lds_dwordx4 v[104:105], off
	s_mov_b32 m0, s71
	s_nop 0
	global_load_lds_dwordx4 v84, s[46:47]
	ds_read_b128 v[104:107], v79
	ds_read_b128 v[108:111], v81 offset:16384
	ds_read_b128 v[112:115], v81 offset:20480
	s_waitcnt lgkmcnt(0)
	v_mfma_f32_32x32x16_bf16 v[48:63], v[104:107], v[108:111], v[48:63]
	s_mov_b32 m0, s84
	v_mfma_f32_32x32x16_bf16 v[32:47], v[104:107], v[112:115], v[32:47]
	ds_read_b128 v[104:107], v79 offset:4096
	s_waitcnt lgkmcnt(0)
	v_mfma_f32_32x32x16_bf16 v[16:31], v[104:107], v[108:111], v[16:31]
	v_mfma_f32_32x32x16_bf16 v[0:15], v[104:107], v[112:115], v[0:15]
	ds_read_b128 v[104:107], v80
	ds_read_b128 v[108:111], v83 offset:16384
	ds_read_b128 v[112:115], v83 offset:20480
	s_waitcnt lgkmcnt(0)
	v_mfma_f32_32x32x16_bf16 v[48:63], v[104:107], v[108:111], v[48:63]
	v_mfma_f32_32x32x16_bf16 v[32:47], v[104:107], v[112:115], v[32:47]
	ds_read_b128 v[104:107], v80 offset:4096
	s_waitcnt lgkmcnt(0)
	v_mfma_f32_32x32x16_bf16 v[16:31], v[104:107], v[108:111], v[16:31]
	v_mfma_f32_32x32x16_bf16 v[0:15], v[104:107], v[112:115], v[0:15]
	ds_read_b128 v[104:107], v82
	ds_read_b128 v[108:111], v85 offset:16384
	ds_read_b128 v[112:115], v85 offset:20480
	s_waitcnt lgkmcnt(0)
	v_mfma_f32_32x32x16_bf16 v[48:63], v[104:107], v[108:111], v[48:63]
	v_mfma_f32_32x32x16_bf16 v[32:47], v[104:107], v[112:115], v[32:47]
	ds_read_b128 v[104:107], v82 offset:4096
	s_waitcnt lgkmcnt(0)
	v_mfma_f32_32x32x16_bf16 v[16:31], v[104:107], v[108:111], v[16:31]
	v_mfma_f32_32x32x16_bf16 v[0:15], v[104:107], v[112:115], v[0:15]
	ds_read_b128 v[104:107], v86
	ds_read_b128 v[108:111], v87 offset:16384
	ds_read_b128 v[112:115], v87 offset:20480
	s_waitcnt lgkmcnt(0)
	v_mfma_f32_32x32x16_bf16 v[48:63], v[104:107], v[108:111], v[48:63]
	v_mfma_f32_32x32x16_bf16 v[32:47], v[104:107], v[112:115], v[32:47]
	ds_read_b128 v[104:107], v86 offset:4096
	s_waitcnt vmcnt(0)
	s_waitcnt vmcnt(0) lgkmcnt(0)
	s_barrier
	v_mfma_f32_32x32x16_bf16 v[16:31], v[104:107], v[108:111], v[16:31]
	v_mfma_f32_32x32x16_bf16 v[0:15], v[104:107], v[112:115], v[0:15]
	v_lshl_add_u64 v[104:105], v[64:65], 0, s[4:5]
	global_load_lds_dwordx4 v[104:105], off
	s_mov_b32 m0, s85
	v_lshl_add_u64 v[104:105], v[66:67], 0, s[4:5]
	global_load_lds_dwordx4 v76, s[48:49]
	s_mov_b32 m0, s86
	s_nop 0
	global_load_lds_dwordx4 v[104:105], off
	s_mov_b32 m0, s87
	v_lshl_add_u64 v[104:105], v[68:69], 0, s[4:5]
	global_load_lds_dwordx4 v77, s[48:49]
	s_mov_b32 m0, s88
	s_nop 0
	global_load_lds_dwordx4 v[104:105], off
	s_mov_b32 m0, s89
	v_lshl_add_u64 v[104:105], v[70:71], 0, s[4:5]
	global_load_lds_dwordx4 v78, s[48:49]
	s_mov_b32 m0, s90
	s_mov_b64 s[4:5], 0x380
	global_load_lds_dwordx4 v[104:105], off
	s_mov_b32 m0, s91
	s_nop 0
	global_load_lds_dwordx4 v84, s[48:49]
	ds_read_b128 v[104:107], v79 offset:32768
	ds_read_b128 v[108:111], v81 offset:49152
	ds_read_b128 v[112:115], v81 offset:53248
	s_waitcnt lgkmcnt(0)
	v_mfma_f32_32x32x16_bf16 v[48:63], v[104:107], v[108:111], v[48:63]
	s_mov_b32 m0, s18
	v_mfma_f32_32x32x16_bf16 v[32:47], v[104:107], v[112:115], v[32:47]
	ds_read_b128 v[104:107], v79 offset:36864
	s_waitcnt lgkmcnt(0)
	v_mfma_f32_32x32x16_bf16 v[16:31], v[104:107], v[108:111], v[16:31]
	v_mfma_f32_32x32x16_bf16 v[0:15], v[104:107], v[112:115], v[0:15]
	ds_read_b128 v[104:107], v80 offset:32768
	ds_read_b128 v[108:111], v83 offset:49152
	ds_read_b128 v[112:115], v83 offset:53248
	s_waitcnt lgkmcnt(0)
	v_mfma_f32_32x32x16_bf16 v[48:63], v[104:107], v[108:111], v[48:63]
	v_mfma_f32_32x32x16_bf16 v[32:47], v[104:107], v[112:115], v[32:47]
	ds_read_b128 v[104:107], v80 offset:36864
	s_waitcnt lgkmcnt(0)
	v_mfma_f32_32x32x16_bf16 v[16:31], v[104:107], v[108:111], v[16:31]
	v_mfma_f32_32x32x16_bf16 v[0:15], v[104:107], v[112:115], v[0:15]
	ds_read_b128 v[104:107], v82 offset:32768
	ds_read_b128 v[108:111], v85 offset:49152
	ds_read_b128 v[112:115], v85 offset:53248
	s_waitcnt lgkmcnt(0)
	v_mfma_f32_32x32x16_bf16 v[48:63], v[104:107], v[108:111], v[48:63]
	v_mfma_f32_32x32x16_bf16 v[32:47], v[104:107], v[112:115], v[32:47]
	ds_read_b128 v[104:107], v82 offset:36864
	s_waitcnt lgkmcnt(0)
	v_mfma_f32_32x32x16_bf16 v[16:31], v[104:107], v[108:111], v[16:31]
	v_mfma_f32_32x32x16_bf16 v[0:15], v[104:107], v[112:115], v[0:15]
	ds_read_b128 v[104:107], v86 offset:32768
	ds_read_b128 v[108:111], v87 offset:49152
	ds_read_b128 v[112:115], v87 offset:53248
	s_waitcnt lgkmcnt(0)
	v_mfma_f32_32x32x16_bf16 v[48:63], v[104:107], v[108:111], v[48:63]
	v_mfma_f32_32x32x16_bf16 v[32:47], v[104:107], v[112:115], v[32:47]
	ds_read_b128 v[104:107], v86 offset:36864
	s_waitcnt vmcnt(0)
	s_waitcnt vmcnt(0) lgkmcnt(0)
	s_barrier
; #define WAIT_V0() asm volatile("s_waitcnt vmcnt(0)" ::: "memory")
; DI void gemm_core(char* smem, int nk, const char* Ab, const char* Bb, const unsigned (&aoff)[4], const unsigned (&boff)[4],
;                   f32x16 (&acc)[2][2]) {
;     ...
;   for (int kt = 0; kt < nk; ++kt) {
;     const int cur = kt & 1;
;     if (kt + 1 < nk) stage(cur ^ 1, kt + 1);
;     const char* sb = smem + cur * STAGE_B;
; #pragma unroll
;     for (int ks = 0; ks < 4; ++ks) {
;       bf16x8 af[2], bfr[2];
; #pragma unroll
;       for (int mb = 0; mb < 2; ++mb) af[mb] = *(const bf16x8*)(sb + a_base + mb * 4096 + xo[ks]);
; #pragma unroll
;       for (int nb = 0; nb < 2; ++nb) bfr[nb] = *(const bf16x8*)(sb + b_base + nb * 4096 + xo[ks]);
; #pragma unroll
;       for (int mb = 0; mb < 2; ++mb)
; #pragma unroll
;         for (int nb = 0; nb < 2; ++nb)
;           acc[mb][nb] = __builtin_amdgcn_mfma_f32_32x32x16_bf16(af[mb], bfr[nb], acc[mb][nb], 0, 0, 0);
;     }
;     WAIT_V0();
;     __syncthreads();
;   }
	v_mfma_f32_32x32x16_bf16 v[16:31], v[104:107], v[108:111], v[16:31]
	v_mfma_f32_32x32x16_bf16 v[0:15], v[104:107], v[112:115], v[0:15]
	v_lshl_add_u64 v[104:105], v[64:65], 0, s[4:5]
	global_load_lds_dwordx4 v[104:105], off
	s_mov_b32 m0, s19
	v_lshl_add_u64 v[104:105], v[66:67], 0, s[4:5]
	global_load_lds_dwordx4 v76, s[50:51]
	s_mov_b32 m0, s22
	s_nop 0
	global_load_lds_dwordx4 v[104:105], off
	s_mov_b32 m0, s23
	v_lshl_add_u64 v[104:105], v[68:69], 0, s[4:5]
	global_load_lds_dwordx4 v77, s[50:51]
	s_mov_b32 m0, s29
	s_nop 0
	global_load_lds_dwordx4 v[104:105], off
	s_mov_b32 m0, s69
	v_lshl_add_u64 v[104:105], v[70:71], 0, s[4:5]
	global_load_lds_dwordx4 v78, s[50:51]
	s_mov_b32 m0, s70
	s_mov_b64 s[4:5], 0x400
	global_load_lds_dwordx4 v[104:105], off
	s_mov_b32 m0, s71
	s_nop 0
	global_load_lds_dwordx4 v84, s[50:51]
	ds_read_b128 v[104:107], v79
	ds_read_b128 v[108:111], v81 offset:16384
	ds_read_b128 v[112:115], v81 offset:20480
	s_waitcnt lgkmcnt(0)
	v_mfma_f32_32x32x16_bf16 v[48:63], v[104:107], v[108:111], v[48:63]
	s_mov_b32 m0, s84
	v_readfirstlane_b32 s84, v89
	v_mfma_f32_32x32x16_bf16 v[32:47], v[104:107], v[112:115], v[32:47]
	ds_read_b128 v[104:107], v79 offset:4096
	s_waitcnt lgkmcnt(0)
	v_mfma_f32_32x32x16_bf16 v[16:31], v[104:107], v[108:111], v[16:31]
	v_mfma_f32_32x32x16_bf16 v[0:15], v[104:107], v[112:115], v[0:15]
	ds_read_b128 v[104:107], v80
	ds_read_b128 v[108:111], v83 offset:16384
	ds_read_b128 v[112:115], v83 offset:20480
	s_waitcnt lgkmcnt(0)
	v_mfma_f32_32x32x16_bf16 v[48:63], v[104:107], v[108:111], v[48:63]
	v_mfma_f32_32x32x16_bf16 v[32:47], v[104:107], v[112:115], v[32:47]
	ds_read_b128 v[104:107], v80 offset:4096
	s_waitcnt lgkmcnt(0)
	v_mfma_f32_32x32x16_bf16 v[16:31], v[104:107], v[108:111], v[16:31]
	v_mfma_f32_32x32x16_bf16 v[0:15], v[104:107], v[112:115], v[0:15]
	ds_read_b128 v[104:107], v82
	ds_read_b128 v[108:111], v85 offset:16384
	ds_read_b128 v[112:115], v85 offset:20480
	s_waitcnt lgkmcnt(0)
	v_mfma_f32_32x32x16_bf16 v[48:63], v[104:107], v[108:111], v[48:63]
	v_mfma_f32_32x32x16_bf16 v[32:47], v[104:107], v[112:115], v[32:47]
	ds_read_b128 v[104:107], v82 offset:4096
	s_waitcnt lgkmcnt(0)
	v_mfma_f32_32x32x16_bf16 v[16:31], v[104:107], v[108:111], v[16:31]
	v_mfma_f32_32x32x16_bf16 v[0:15], v[104:107], v[112:115], v[0:15]
	ds_read_b128 v[104:107], v86
	ds_read_b128 v[108:111], v87 offset:16384
	ds_read_b128 v[112:115], v87 offset:20480
	s_waitcnt lgkmcnt(0)
	v_mfma_f32_32x32x16_bf16 v[48:63], v[104:107], v[108:111], v[48:63]
	v_mfma_f32_32x32x16_bf16 v[32:47], v[104:107], v[112:115], v[32:47]
	ds_read_b128 v[104:107], v86 offset:4096
	s_waitcnt vmcnt(0)
	s_waitcnt vmcnt(0) lgkmcnt(0)
	s_barrier
	v_mfma_f32_32x32x16_bf16 v[16:31], v[104:107], v[108:111], v[16:31]
	v_mfma_f32_32x32x16_bf16 v[0:15], v[104:107], v[112:115], v[0:15]
	v_lshl_add_u64 v[104:105], v[64:65], 0, s[4:5]
	global_load_lds_dwordx4 v[104:105], off
	s_mov_b32 m0, s85
	v_lshl_add_u64 v[104:105], v[66:67], 0, s[4:5]
	global_load_lds_dwordx4 v76, s[52:53]
	s_mov_b32 m0, s86
	v_readfirstlane_b32 s85, v88
	global_load_lds_dwordx4 v[104:105], off
	s_mov_b32 m0, s87
	v_lshl_add_u64 v[104:105], v[68:69], 0, s[4:5]
	global_load_lds_dwordx4 v77, s[52:53]
	s_mov_b32 m0, s88
	v_readfirstlane_b32 s86, v90
	global_load_lds_dwordx4 v[104:105], off
	s_mov_b32 m0, s89
	v_lshl_add_u64 v[104:105], v[70:71], 0, s[4:5]
	global_load_lds_dwordx4 v78, s[52:53]
	s_mov_b32 m0, s90
	s_mov_b64 s[4:5], 0x480
	global_load_lds_dwordx4 v[104:105], off
	s_mov_b32 m0, s91
	v_readfirstlane_b32 s87, v91
	global_load_lds_dwordx4 v84, s[52:53]
	ds_read_b128 v[104:107], v79 offset:32768
	ds_read_b128 v[108:111], v81 offset:49152
	ds_read_b128 v[112:115], v81 offset:53248
	s_waitcnt lgkmcnt(0)
	v_mfma_f32_32x32x16_bf16 v[48:63], v[104:107], v[108:111], v[48:63]
	s_mov_b32 m0, s18
	v_readfirstlane_b32 s18, v97
	v_readfirstlane_b32 s88, v92
	v_readfirstlane_b32 s89, v93
	v_readfirstlane_b32 s90, v94
	v_readfirstlane_b32 s91, v95
	v_mfma_f32_32x32x16_bf16 v[32:47], v[104:107], v[112:115], v[32:47]
	ds_read_b128 v[104:107], v79 offset:36864
	s_waitcnt lgkmcnt(0)
	v_mfma_f32_32x32x16_bf16 v[16:31], v[104:107], v[108:111], v[16:31]
	v_mfma_f32_32x32x16_bf16 v[0:15], v[104:107], v[112:115], v[0:15]
	ds_read_b128 v[104:107], v80 offset:32768
	ds_read_b128 v[108:111], v83 offset:49152
	ds_read_b128 v[112:115], v83 offset:53248
	s_waitcnt lgkmcnt(0)
	v_mfma_f32_32x32x16_bf16 v[48:63], v[104:107], v[108:111], v[48:63]
	v_mfma_f32_32x32x16_bf16 v[32:47], v[104:107], v[112:115], v[32:47]
	ds_read_b128 v[104:107], v80 offset:36864
	s_waitcnt lgkmcnt(0)
	v_mfma_f32_32x32x16_bf16 v[16:31], v[104:107], v[108:111], v[16:31]
	v_mfma_f32_32x32x16_bf16 v[0:15], v[104:107], v[112:115], v[0:15]
	ds_read_b128 v[104:107], v82 offset:32768
	ds_read_b128 v[108:111], v85 offset:49152
	ds_read_b128 v[112:115], v85 offset:53248
	s_waitcnt lgkmcnt(0)
	v_mfma_f32_32x32x16_bf16 v[48:63], v[104:107], v[108:111], v[48:63]
	v_mfma_f32_32x32x16_bf16 v[32:47], v[104:107], v[112:115], v[32:47]
	ds_read_b128 v[104:107], v82 offset:36864
	s_waitcnt lgkmcnt(0)
	v_mfma_f32_32x32x16_bf16 v[16:31], v[104:107], v[108:111], v[16:31]
	v_mfma_f32_32x32x16_bf16 v[0:15], v[104:107], v[112:115], v[0:15]
	ds_read_b128 v[104:107], v86 offset:32768
	ds_read_b128 v[108:111], v87 offset:49152
	ds_read_b128 v[112:115], v87 offset:53248
	s_waitcnt lgkmcnt(0)
	v_mfma_f32_32x32x16_bf16 v[48:63], v[104:107], v[108:111], v[48:63]
	v_mfma_f32_32x32x16_bf16 v[32:47], v[104:107], v[112:115], v[32:47]
	ds_read_b128 v[104:107], v86 offset:36864
	s_waitcnt vmcnt(0)
	s_waitcnt vmcnt(0) lgkmcnt(0)
	s_barrier
; #define WAIT_V0() asm volatile("s_waitcnt vmcnt(0)" ::: "memory")
; DI void gemm_core(char* smem, int nk, const char* Ab, const char* Bb, const unsigned (&aoff)[4], const unsigned (&boff)[4],
;                   f32x16 (&acc)[2][2]) {
;     ...
;   for (int kt = 0; kt < nk; ++kt) {
;     const int cur = kt & 1;
;     if (kt + 1 < nk) stage(cur ^ 1, kt + 1);
;     const char* sb = smem + cur * STAGE_B;
; #pragma unroll
;     for (int ks = 0; ks < 4; ++ks) {
;       bf16x8 af[2], bfr[2];
; #pragma unroll
;       for (int mb = 0; mb < 2; ++mb) af[mb] = *(const bf16x8*)(sb + a_base + mb * 4096 + xo[ks]);
; #pragma unroll
;       for (int nb = 0; nb < 2; ++nb) bfr[nb] = *(const bf16x8*)(sb + b_base + nb * 4096 + xo[ks]);
; #pragma unroll
;       for (int mb = 0; mb < 2; ++mb)
; #pragma unroll
;         for (int nb = 0; nb < 2; ++nb)
;           acc[mb][nb] = __builtin_amdgcn_mfma_f32_32x32x16_bf16(af[mb], bfr[nb], acc[mb][nb], 0, 0, 0);
;     }
;     WAIT_V0();
;     __syncthreads();
;   }
	v_mfma_f32_32x32x16_bf16 v[16:31], v[104:107], v[108:111], v[16:31]
	v_mfma_f32_32x32x16_bf16 v[0:15], v[104:107], v[112:115], v[0:15]
	v_lshl_add_u64 v[104:105], v[64:65], 0, s[4:5]
	global_load_lds_dwordx4 v[104:105], off
	s_mov_b32 m0, s19
	v_lshl_add_u64 v[104:105], v[66:67], 0, s[4:5]
	global_load_lds_dwordx4 v76, s[54:55]
	s_mov_b32 m0, s22
	v_readfirstlane_b32 s19, v96
	global_load_lds_dwordx4 v[104:105], off
	s_mov_b32 m0, s23
	v_lshl_add_u64 v[104:105], v[68:69], 0, s[4:5]
	global_load_lds_dwordx4 v77, s[54:55]
	s_mov_b32 m0, s29
	v_readfirstlane_b32 s22, v98
	global_load_lds_dwordx4 v[104:105], off
	s_mov_b32 m0, s69
	v_lshl_add_u64 v[104:105], v[70:71], 0, s[4:5]
	global_load_lds_dwordx4 v78, s[54:55]
	s_mov_b32 m0, s70
	s_mov_b64 s[4:5], 0x500
	global_load_lds_dwordx4 v[104:105], off
	s_mov_b32 m0, s71
	v_lshl_add_u64 v[96:97], v[66:67], 0, s[4:5]
	global_load_lds_dwordx4 v84, s[54:55]
	ds_read_b128 v[104:107], v79
	ds_read_b128 v[108:111], v81 offset:16384
	ds_read_b128 v[112:115], v81 offset:20480
	s_waitcnt lgkmcnt(0)
	v_mfma_f32_32x32x16_bf16 v[48:63], v[104:107], v[108:111], v[48:63]
	s_mov_b32 m0, s18
	v_readfirstlane_b32 s23, v99
	v_readfirstlane_b32 s29, v100
	v_readfirstlane_b32 s69, v101
	v_readfirstlane_b32 s70, v102
	v_readfirstlane_b32 s71, v103
	v_mfma_f32_32x32x16_bf16 v[32:47], v[104:107], v[112:115], v[32:47]
	ds_read_b128 v[104:107], v79 offset:4096
	s_waitcnt lgkmcnt(0)
	v_mfma_f32_32x32x16_bf16 v[16:31], v[104:107], v[108:111], v[16:31]
	v_mfma_f32_32x32x16_bf16 v[0:15], v[104:107], v[112:115], v[0:15]
	ds_read_b128 v[104:107], v80
	ds_read_b128 v[108:111], v83 offset:16384
	ds_read_b128 v[112:115], v83 offset:20480
	s_waitcnt lgkmcnt(0)
	v_mfma_f32_32x32x16_bf16 v[48:63], v[104:107], v[108:111], v[48:63]
	v_mfma_f32_32x32x16_bf16 v[32:47], v[104:107], v[112:115], v[32:47]
	ds_read_b128 v[104:107], v80 offset:4096
	s_waitcnt lgkmcnt(0)
	v_mfma_f32_32x32x16_bf16 v[16:31], v[104:107], v[108:111], v[16:31]
	v_mfma_f32_32x32x16_bf16 v[0:15], v[104:107], v[112:115], v[0:15]
	ds_read_b128 v[104:107], v82
	ds_read_b128 v[108:111], v85 offset:16384
	ds_read_b128 v[112:115], v85 offset:20480
	s_waitcnt lgkmcnt(0)
	v_mfma_f32_32x32x16_bf16 v[48:63], v[104:107], v[108:111], v[48:63]
	v_mfma_f32_32x32x16_bf16 v[32:47], v[104:107], v[112:115], v[32:47]
	ds_read_b128 v[104:107], v82 offset:4096
	s_waitcnt lgkmcnt(0)
	v_mfma_f32_32x32x16_bf16 v[16:31], v[104:107], v[108:111], v[16:31]
	v_mfma_f32_32x32x16_bf16 v[0:15], v[104:107], v[112:115], v[0:15]
	ds_read_b128 v[104:107], v86
	ds_read_b128 v[108:111], v87 offset:16384
	ds_read_b128 v[112:115], v87 offset:20480
	s_waitcnt lgkmcnt(0)
	v_mfma_f32_32x32x16_bf16 v[48:63], v[104:107], v[108:111], v[48:63]
	v_mfma_f32_32x32x16_bf16 v[32:47], v[104:107], v[112:115], v[32:47]
	ds_read_b128 v[104:107], v86 offset:4096
	s_waitcnt vmcnt(0)
	s_waitcnt vmcnt(0) lgkmcnt(0)
	s_barrier
	v_mfma_f32_32x32x16_bf16 v[16:31], v[104:107], v[108:111], v[16:31]
	v_mfma_f32_32x32x16_bf16 v[0:15], v[104:107], v[112:115], v[0:15]
	v_lshl_add_u64 v[104:105], v[64:65], 0, s[4:5]
	global_load_lds_dwordx4 v[104:105], off
	s_mov_b32 m0, s19
	s_nop 0
	global_load_lds_dwordx4 v76, s[56:57]
	s_mov_b32 m0, s22
	s_nop 0
	global_load_lds_dwordx4 v[96:97], off
	s_mov_b32 m0, s23
	v_lshl_add_u64 v[96:97], v[68:69], 0, s[4:5]
	global_load_lds_dwordx4 v77, s[56:57]
	s_mov_b32 m0, s29
	s_nop 0
	global_load_lds_dwordx4 v[96:97], off
	s_mov_b32 m0, s69
	v_lshl_add_u64 v[96:97], v[70:71], 0, s[4:5]
	global_load_lds_dwordx4 v78, s[56:57]
	s_mov_b32 m0, s70
	s_mov_b64 s[4:5], 0x580
	global_load_lds_dwordx4 v[96:97], off
	s_mov_b32 m0, s71
	v_lshl_add_u64 v[88:89], v[66:67], 0, s[4:5]
	global_load_lds_dwordx4 v84, s[56:57]
	ds_read_b128 v[96:99], v79 offset:32768
	ds_read_b128 v[100:103], v81 offset:49152
	ds_read_b128 v[104:107], v81 offset:53248
	s_waitcnt lgkmcnt(0)
	v_mfma_f32_32x32x16_bf16 v[48:63], v[96:99], v[100:103], v[48:63]
	s_mov_b32 m0, s84
	v_mfma_f32_32x32x16_bf16 v[32:47], v[96:99], v[104:107], v[32:47]
	ds_read_b128 v[96:99], v79 offset:36864
	s_waitcnt lgkmcnt(0)
	v_mfma_f32_32x32x16_bf16 v[16:31], v[96:99], v[100:103], v[16:31]
	v_mfma_f32_32x32x16_bf16 v[0:15], v[96:99], v[104:107], v[0:15]
	ds_read_b128 v[96:99], v80 offset:32768
	ds_read_b128 v[100:103], v83 offset:49152
	ds_read_b128 v[104:107], v83 offset:53248
	s_waitcnt lgkmcnt(0)
	v_mfma_f32_32x32x16_bf16 v[48:63], v[96:99], v[100:103], v[48:63]
	v_mfma_f32_32x32x16_bf16 v[32:47], v[96:99], v[104:107], v[32:47]
	ds_read_b128 v[96:99], v80 offset:36864
	s_waitcnt lgkmcnt(0)
	v_mfma_f32_32x32x16_bf16 v[16:31], v[96:99], v[100:103], v[16:31]
	v_mfma_f32_32x32x16_bf16 v[0:15], v[96:99], v[104:107], v[0:15]
	ds_read_b128 v[96:99], v82 offset:32768
	ds_read_b128 v[100:103], v85 offset:49152
	ds_read_b128 v[104:107], v85 offset:53248
	s_waitcnt lgkmcnt(0)
	v_mfma_f32_32x32x16_bf16 v[48:63], v[96:99], v[100:103], v[48:63]
	v_mfma_f32_32x32x16_bf16 v[32:47], v[96:99], v[104:107], v[32:47]
	ds_read_b128 v[96:99], v82 offset:36864
	s_waitcnt lgkmcnt(0)
	v_mfma_f32_32x32x16_bf16 v[16:31], v[96:99], v[100:103], v[16:31]
	v_mfma_f32_32x32x16_bf16 v[0:15], v[96:99], v[104:107], v[0:15]
	ds_read_b128 v[96:99], v86 offset:32768
	ds_read_b128 v[100:103], v87 offset:49152
	ds_read_b128 v[104:107], v87 offset:53248
	s_waitcnt lgkmcnt(0)
	v_mfma_f32_32x32x16_bf16 v[48:63], v[96:99], v[100:103], v[48:63]
	v_mfma_f32_32x32x16_bf16 v[32:47], v[96:99], v[104:107], v[32:47]
	ds_read_b128 v[96:99], v86 offset:36864
	s_waitcnt vmcnt(0)
	s_waitcnt vmcnt(0) lgkmcnt(0)
	s_barrier
; #define WAIT_V0() asm volatile("s_waitcnt vmcnt(0)" ::: "memory")
; DI void gemm_core(char* smem, int nk, const char* Ab, const char* Bb, const unsigned (&aoff)[4], const unsigned (&boff)[4],
;                   f32x16 (&acc)[2][2]) {
;     ...
;   for (int kt = 0; kt < nk; ++kt) {
;     const int cur = kt & 1;
;     if (kt + 1 < nk) stage(cur ^ 1, kt + 1);
;     const char* sb = smem + cur * STAGE_B;
; #pragma unroll
;     for (int ks = 0; ks < 4; ++ks) {
;       bf16x8 af[2], bfr[2];
; #pragma unroll
;       for (int mb = 0; mb < 2; ++mb) af[mb] = *(const bf16x8*)(sb + a_base + mb * 4096 + xo[ks]);
; #pragma unroll
;       for (int nb = 0; nb < 2; ++nb) bfr[nb] = *(const bf16x8*)(sb + b_base + nb * 4096 + xo[ks]);
; #pragma unroll
;       for (int mb = 0; mb < 2; ++mb)
; #pragma unroll
;         for (int nb = 0; nb < 2; ++nb)
;           acc[mb][nb] = __builtin_amdgcn_mfma_f32_32x32x16_bf16(af[mb], bfr[nb], acc[mb][nb], 0, 0, 0);
;     }
;     WAIT_V0();
;     __syncthreads();
;   }
	v_mfma_f32_32x32x16_bf16 v[16:31], v[96:99], v[100:103], v[16:31]
	v_mfma_f32_32x32x16_bf16 v[0:15], v[96:99], v[104:107], v[0:15]
	v_lshl_add_u64 v[96:97], v[64:65], 0, s[4:5]
	global_load_lds_dwordx4 v[96:97], off
	s_mov_b32 m0, s85
	s_nop 0
	global_load_lds_dwordx4 v76, s[58:59]
	s_mov_b32 m0, s86
	s_nop 0
	global_load_lds_dwordx4 v[88:89], off
	s_mov_b32 m0, s87
	v_lshl_add_u64 v[88:89], v[68:69], 0, s[4:5]
	global_load_lds_dwordx4 v77, s[58:59]
	s_mov_b32 m0, s88
	s_nop 0
	global_load_lds_dwordx4 v[88:89], off
	s_mov_b32 m0, s89
	v_lshl_add_u64 v[88:89], v[70:71], 0, s[4:5]
	global_load_lds_dwordx4 v78, s[58:59]
	s_mov_b32 m0, s90
	s_mov_b64 s[4:5], 0x600
	global_load_lds_dwordx4 v[88:89], off
	s_mov_b32 m0, s91
	s_nop 0
	global_load_lds_dwordx4 v84, s[58:59]
	ds_read_b128 v[88:91], v79
	ds_read_b128 v[92:95], v81 offset:16384
	ds_read_b128 v[96:99], v81 offset:20480
	s_waitcnt lgkmcnt(0)
	v_mfma_f32_32x32x16_bf16 v[48:63], v[88:91], v[92:95], v[48:63]
	s_mov_b32 m0, s18
	v_mfma_f32_32x32x16_bf16 v[32:47], v[88:91], v[96:99], v[32:47]
	ds_read_b128 v[88:91], v79 offset:4096
	s_waitcnt lgkmcnt(0)
	v_mfma_f32_32x32x16_bf16 v[16:31], v[88:91], v[92:95], v[16:31]
	v_mfma_f32_32x32x16_bf16 v[0:15], v[88:91], v[96:99], v[0:15]
	ds_read_b128 v[88:91], v80
	ds_read_b128 v[92:95], v83 offset:16384
	ds_read_b128 v[96:99], v83 offset:20480
	s_waitcnt lgkmcnt(0)
	v_mfma_f32_32x32x16_bf16 v[48:63], v[88:91], v[92:95], v[48:63]
	v_mfma_f32_32x32x16_bf16 v[32:47], v[88:91], v[96:99], v[32:47]
	ds_read_b128 v[88:91], v80 offset:4096
	s_waitcnt lgkmcnt(0)
	v_mfma_f32_32x32x16_bf16 v[16:31], v[88:91], v[92:95], v[16:31]
	v_mfma_f32_32x32x16_bf16 v[0:15], v[88:91], v[96:99], v[0:15]
	ds_read_b128 v[88:91], v82
	ds_read_b128 v[92:95], v85 offset:16384
	ds_read_b128 v[96:99], v85 offset:20480
	s_waitcnt lgkmcnt(0)
	v_mfma_f32_32x32x16_bf16 v[48:63], v[88:91], v[92:95], v[48:63]
	v_mfma_f32_32x32x16_bf16 v[32:47], v[88:91], v[96:99], v[32:47]
	ds_read_b128 v[88:91], v82 offset:4096
	s_waitcnt lgkmcnt(0)
	v_mfma_f32_32x32x16_bf16 v[16:31], v[88:91], v[92:95], v[16:31]
	v_mfma_f32_32x32x16_bf16 v[0:15], v[88:91], v[96:99], v[0:15]
	ds_read_b128 v[88:91], v86
	ds_read_b128 v[92:95], v87 offset:16384
	ds_read_b128 v[96:99], v87 offset:20480
	s_waitcnt lgkmcnt(0)
	v_mfma_f32_32x32x16_bf16 v[48:63], v[88:91], v[92:95], v[48:63]
	v_mfma_f32_32x32x16_bf16 v[32:47], v[88:91], v[96:99], v[32:47]
	ds_read_b128 v[88:91], v86 offset:4096
	s_waitcnt vmcnt(0)
	s_waitcnt vmcnt(0) lgkmcnt(0)
	s_barrier
	v_mfma_f32_32x32x16_bf16 v[16:31], v[88:91], v[92:95], v[16:31]
	v_mfma_f32_32x32x16_bf16 v[0:15], v[88:91], v[96:99], v[0:15]
	v_lshl_add_u64 v[88:89], v[64:65], 0, s[4:5]
	global_load_lds_dwordx4 v[88:89], off
	s_mov_b32 m0, s19
	v_lshl_add_u64 v[88:89], v[66:67], 0, s[4:5]
	global_load_lds_dwordx4 v76, s[60:61]
	s_mov_b32 m0, s22
	s_nop 0
	global_load_lds_dwordx4 v[88:89], off
	s_mov_b32 m0, s23
	v_lshl_add_u64 v[88:89], v[68:69], 0, s[4:5]
	global_load_lds_dwordx4 v77, s[60:61]
	s_mov_b32 m0, s29
	s_nop 0
	global_load_lds_dwordx4 v[88:89], off
	s_mov_b32 m0, s69
	v_lshl_add_u64 v[88:89], v[70:71], 0, s[4:5]
	global_load_lds_dwordx4 v78, s[60:61]
	s_mov_b32 m0, s70
	s_mov_b64 s[4:5], 0x680
	global_load_lds_dwordx4 v[88:89], off
	s_mov_b32 m0, s71
	s_nop 0
	global_load_lds_dwordx4 v84, s[60:61]
	ds_read_b128 v[88:91], v79 offset:32768
	ds_read_b128 v[92:95], v81 offset:49152
	ds_read_b128 v[96:99], v81 offset:53248
	s_waitcnt lgkmcnt(0)
	v_mfma_f32_32x32x16_bf16 v[48:63], v[88:91], v[92:95], v[48:63]
	s_mov_b32 m0, s84
	v_mfma_f32_32x32x16_bf16 v[32:47], v[88:91], v[96:99], v[32:47]
	ds_read_b128 v[88:91], v79 offset:36864
	s_waitcnt lgkmcnt(0)
	v_mfma_f32_32x32x16_bf16 v[16:31], v[88:91], v[92:95], v[16:31]
	v_mfma_f32_32x32x16_bf16 v[0:15], v[88:91], v[96:99], v[0:15]
	ds_read_b128 v[88:91], v80 offset:32768
	ds_read_b128 v[92:95], v83 offset:49152
	ds_read_b128 v[96:99], v83 offset:53248
	s_waitcnt lgkmcnt(0)
	v_mfma_f32_32x32x16_bf16 v[48:63], v[88:91], v[92:95], v[48:63]
	v_mfma_f32_32x32x16_bf16 v[32:47], v[88:91], v[96:99], v[32:47]
	ds_read_b128 v[88:91], v80 offset:36864
	s_waitcnt lgkmcnt(0)
	v_mfma_f32_32x32x16_bf16 v[16:31], v[88:91], v[92:95], v[16:31]
	v_mfma_f32_32x32x16_bf16 v[0:15], v[88:91], v[96:99], v[0:15]
	ds_read_b128 v[88:91], v82 offset:32768
	ds_read_b128 v[92:95], v85 offset:49152
	ds_read_b128 v[96:99], v85 offset:53248
	s_waitcnt lgkmcnt(0)
	v_mfma_f32_32x32x16_bf16 v[48:63], v[88:91], v[92:95], v[48:63]
	v_mfma_f32_32x32x16_bf16 v[32:47], v[88:91], v[96:99], v[32:47]
	ds_read_b128 v[88:91], v82 offset:36864
	s_waitcnt lgkmcnt(0)
	v_mfma_f32_32x32x16_bf16 v[16:31], v[88:91], v[92:95], v[16:31]
	v_mfma_f32_32x32x16_bf16 v[0:15], v[88:91], v[96:99], v[0:15]
	ds_read_b128 v[88:91], v86 offset:32768
	ds_read_b128 v[92:95], v87 offset:49152
	ds_read_b128 v[96:99], v87 offset:53248
	s_waitcnt lgkmcnt(0)
	v_mfma_f32_32x32x16_bf16 v[48:63], v[88:91], v[92:95], v[48:63]
	v_mfma_f32_32x32x16_bf16 v[32:47], v[88:91], v[96:99], v[32:47]
	ds_read_b128 v[88:91], v86 offset:36864
	s_waitcnt vmcnt(0)
	s_waitcnt vmcnt(0) lgkmcnt(0)
	s_barrier
; #define WAIT_V0() asm volatile("s_waitcnt vmcnt(0)" ::: "memory")
; DI void gemm_core(char* smem, int nk, const char* Ab, const char* Bb, const unsigned (&aoff)[4], const unsigned (&boff)[4],
;                   f32x16 (&acc)[2][2]) {
;     ...
;   for (int kt = 0; kt < nk; ++kt) {
;     const int cur = kt & 1;
;     if (kt + 1 < nk) stage(cur ^ 1, kt + 1);
;     const char* sb = smem + cur * STAGE_B;
; #pragma unroll
;     for (int ks = 0; ks < 4; ++ks) {
;       bf16x8 af[2], bfr[2];
; #pragma unroll
;       for (int mb = 0; mb < 2; ++mb) af[mb] = *(const bf16x8*)(sb + a_base + mb * 4096 + xo[ks]);
; #pragma unroll
;       for (int nb = 0; nb < 2; ++nb) bfr[nb] = *(const bf16x8*)(sb + b_base + nb * 4096 + xo[ks]);
; #pragma unroll
;       for (int mb = 0; mb < 2; ++mb)
; #pragma unroll
;         for (int nb = 0; nb < 2; ++nb)
;           acc[mb][nb] = __builtin_amdgcn_mfma_f32_32x32x16_bf16(af[mb], bfr[nb], acc[mb][nb], 0, 0, 0);
;     }
;     WAIT_V0();
;     __syncthreads();
;   }
	v_mfma_f32_32x32x16_bf16 v[16:31], v[88:91], v[92:95], v[16:31]
	v_mfma_f32_32x32x16_bf16 v[0:15], v[88:91], v[96:99], v[0:15]
	v_lshl_add_u64 v[88:89], v[64:65], 0, s[4:5]
	global_load_lds_dwordx4 v[88:89], off
	s_mov_b32 m0, s85
	v_lshl_add_u64 v[88:89], v[66:67], 0, s[4:5]
	global_load_lds_dwordx4 v76, s[62:63]
	s_mov_b32 m0, s86
	s_nop 0
	global_load_lds_dwordx4 v[88:89], off
	s_mov_b32 m0, s87
	v_lshl_add_u64 v[88:89], v[68:69], 0, s[4:5]
	global_load_lds_dwordx4 v77, s[62:63]
	s_mov_b32 m0, s88
	s_nop 0
	global_load_lds_dwordx4 v[88:89], off
	s_mov_b32 m0, s89
	v_lshl_add_u64 v[88:89], v[70:71], 0, s[4:5]
	global_load_lds_dwordx4 v78, s[62:63]
	s_mov_b32 m0, s90
	s_mov_b64 s[4:5], 0x700
	global_load_lds_dwordx4 v[88:89], off
	s_mov_b32 m0, s91
	s_nop 0
	global_load_lds_dwordx4 v84, s[62:63]
	ds_read_b128 v[88:91], v79
	ds_read_b128 v[92:95], v81 offset:16384
	ds_read_b128 v[96:99], v81 offset:20480
	s_waitcnt lgkmcnt(0)
	v_mfma_f32_32x32x16_bf16 v[48:63], v[88:91], v[92:95], v[48:63]
	s_mov_b32 m0, s18
	v_mfma_f32_32x32x16_bf16 v[32:47], v[88:91], v[96:99], v[32:47]
	ds_read_b128 v[88:91], v79 offset:4096
	s_waitcnt lgkmcnt(0)
	v_mfma_f32_32x32x16_bf16 v[16:31], v[88:91], v[92:95], v[16:31]
	v_mfma_f32_32x32x16_bf16 v[0:15], v[88:91], v[96:99], v[0:15]
	ds_read_b128 v[88:91], v80
	ds_read_b128 v[92:95], v83 offset:16384
	ds_read_b128 v[96:99], v83 offset:20480
	s_waitcnt lgkmcnt(0)
	v_mfma_f32_32x32x16_bf16 v[48:63], v[88:91], v[92:95], v[48:63]
	v_mfma_f32_32x32x16_bf16 v[32:47], v[88:91], v[96:99], v[32:47]
	ds_read_b128 v[88:91], v80 offset:4096
	s_waitcnt lgkmcnt(0)
	v_mfma_f32_32x32x16_bf16 v[16:31], v[88:91], v[92:95], v[16:31]
	v_mfma_f32_32x32x16_bf16 v[0:15], v[88:91], v[96:99], v[0:15]
	ds_read_b128 v[88:91], v82
	ds_read_b128 v[92:95], v85 offset:16384
	ds_read_b128 v[96:99], v85 offset:20480
	s_waitcnt lgkmcnt(0)
	v_mfma_f32_32x32x16_bf16 v[48:63], v[88:91], v[92:95], v[48:63]
	v_mfma_f32_32x32x16_bf16 v[32:47], v[88:91], v[96:99], v[32:47]
	ds_read_b128 v[88:91], v82 offset:4096
	s_waitcnt lgkmcnt(0)
	v_mfma_f32_32x32x16_bf16 v[16:31], v[88:91], v[92:95], v[16:31]
	v_mfma_f32_32x32x16_bf16 v[0:15], v[88:91], v[96:99], v[0:15]
	ds_read_b128 v[88:91], v86
	ds_read_b128 v[92:95], v87 offset:16384
	ds_read_b128 v[96:99], v87 offset:20480
	s_waitcnt lgkmcnt(0)
	v_mfma_f32_32x32x16_bf16 v[48:63], v[88:91], v[92:95], v[48:63]
	v_mfma_f32_32x32x16_bf16 v[32:47], v[88:91], v[96:99], v[32:47]
	ds_read_b128 v[88:91], v86 offset:4096
	s_waitcnt vmcnt(0)
	s_waitcnt vmcnt(0) lgkmcnt(0)
	s_barrier
	v_mfma_f32_32x32x16_bf16 v[16:31], v[88:91], v[92:95], v[16:31]
	v_mfma_f32_32x32x16_bf16 v[0:15], v[88:91], v[96:99], v[0:15]
	v_lshl_add_u64 v[88:89], v[64:65], 0, s[4:5]
	global_load_lds_dwordx4 v[88:89], off
	s_mov_b32 m0, s19
	v_lshl_add_u64 v[88:89], v[66:67], 0, s[4:5]
	global_load_lds_dwordx4 v76, s[64:65]
	s_mov_b32 m0, s22
	s_nop 0
	global_load_lds_dwordx4 v[88:89], off
	s_mov_b32 m0, s23
	v_lshl_add_u64 v[88:89], v[68:69], 0, s[4:5]
	global_load_lds_dwordx4 v77, s[64:65]
	s_mov_b32 m0, s29
	s_nop 0
	global_load_lds_dwordx4 v[88:89], off
	s_mov_b32 m0, s69
	v_lshl_add_u64 v[88:89], v[70:71], 0, s[4:5]
	global_load_lds_dwordx4 v78, s[64:65]
	s_mov_b32 m0, s70
	s_mov_b64 s[4:5], 0x780
	global_load_lds_dwordx4 v[88:89], off
	s_mov_b32 m0, s71
	v_lshl_add_u64 v[64:65], v[64:65], 0, s[4:5]
	global_load_lds_dwordx4 v84, s[64:65]
	ds_read_b128 v[88:91], v79 offset:32768
	ds_read_b128 v[92:95], v81 offset:49152
	ds_read_b128 v[96:99], v81 offset:53248
	s_waitcnt lgkmcnt(0)
	v_mfma_f32_32x32x16_bf16 v[48:63], v[88:91], v[92:95], v[48:63]
	s_mov_b32 m0, s84
	s_movk_i32 s4, 0x4000
	v_mfma_f32_32x32x16_bf16 v[32:47], v[88:91], v[96:99], v[32:47]
	ds_read_b128 v[88:91], v79 offset:36864
	s_waitcnt lgkmcnt(0)
	v_mfma_f32_32x32x16_bf16 v[16:31], v[88:91], v[92:95], v[16:31]
	v_mfma_f32_32x32x16_bf16 v[0:15], v[88:91], v[96:99], v[0:15]
	ds_read_b128 v[88:91], v80 offset:32768
	ds_read_b128 v[92:95], v83 offset:49152
	ds_read_b128 v[96:99], v83 offset:53248
	s_waitcnt lgkmcnt(0)
	v_mfma_f32_32x32x16_bf16 v[48:63], v[88:91], v[92:95], v[48:63]
	v_mfma_f32_32x32x16_bf16 v[32:47], v[88:91], v[96:99], v[32:47]
	ds_read_b128 v[88:91], v80 offset:36864
	s_waitcnt lgkmcnt(0)
	v_mfma_f32_32x32x16_bf16 v[16:31], v[88:91], v[92:95], v[16:31]
	v_mfma_f32_32x32x16_bf16 v[0:15], v[88:91], v[96:99], v[0:15]
	ds_read_b128 v[88:91], v82 offset:32768
	ds_read_b128 v[92:95], v85 offset:49152
	ds_read_b128 v[96:99], v85 offset:53248
	s_waitcnt lgkmcnt(0)
	v_mfma_f32_32x32x16_bf16 v[48:63], v[88:91], v[92:95], v[48:63]
	v_mfma_f32_32x32x16_bf16 v[32:47], v[88:91], v[96:99], v[32:47]
	ds_read_b128 v[88:91], v82 offset:36864
	s_waitcnt lgkmcnt(0)
	v_mfma_f32_32x32x16_bf16 v[16:31], v[88:91], v[92:95], v[16:31]
	v_mfma_f32_32x32x16_bf16 v[0:15], v[88:91], v[96:99], v[0:15]
	ds_read_b128 v[88:91], v86 offset:32768
	ds_read_b128 v[92:95], v87 offset:49152
	ds_read_b128 v[96:99], v87 offset:53248
	s_waitcnt lgkmcnt(0)
	v_mfma_f32_32x32x16_bf16 v[48:63], v[88:91], v[92:95], v[48:63]
	v_mfma_f32_32x32x16_bf16 v[32:47], v[88:91], v[96:99], v[32:47]
	ds_read_b128 v[88:91], v86 offset:36864
	s_waitcnt vmcnt(0)
	s_waitcnt vmcnt(0) lgkmcnt(0)
	s_barrier
; #define WAIT_V0() asm volatile("s_waitcnt vmcnt(0)" ::: "memory")
; DI void gemm_core(char* smem, int nk, const char* Ab, const char* Bb, const unsigned (&aoff)[4], const unsigned (&boff)[4],
;                   f32x16 (&acc)[2][2]) {
;     ...
;   for (int kt = 0; kt < nk; ++kt) {
;     const int cur = kt & 1;
;     if (kt + 1 < nk) stage(cur ^ 1, kt + 1);
;     const char* sb = smem + cur * STAGE_B;
; #pragma unroll
;     for (int ks = 0; ks < 4; ++ks) {
;       bf16x8 af[2], bfr[2];
; #pragma unroll
;       for (int mb = 0; mb < 2; ++mb) af[mb] = *(const bf16x8*)(sb + a_base + mb * 4096 + xo[ks]);
; #pragma unroll
;       for (int nb = 0; nb < 2; ++nb) bfr[nb] = *(const bf16x8*)(sb + b_base + nb * 4096 + xo[ks]);
; #pragma unroll
;       for (int mb = 0; mb < 2; ++mb)
; #pragma unroll
;         for (int nb = 0; nb < 2; ++nb)
;           acc[mb][nb] = __builtin_amdgcn_mfma_f32_32x32x16_bf16(af[mb], bfr[nb], acc[mb][nb], 0, 0, 0);
;     }
;     WAIT_V0();
;     __syncthreads();
;   }
	global_load_lds_dwordx4 v[64:65], off
	s_mov_b32 m0, s85
	v_lshl_add_u64 v[64:65], v[66:67], 0, s[6:7]
	global_load_lds_dwordx4 v76, s[66:67]
	s_mov_b32 m0, s86
	v_mfma_f32_32x32x16_bf16 v[16:31], v[88:91], v[92:95], v[16:31]
	global_load_lds_dwordx4 v[64:65], off
	s_mov_b32 m0, s87
	v_lshl_add_u64 v[64:65], v[68:69], 0, s[6:7]
	global_load_lds_dwordx4 v77, s[66:67]
	s_mov_b32 m0, s88
	v_mfma_f32_32x32x16_bf16 v[0:15], v[88:91], v[96:99], v[0:15]
	global_load_lds_dwordx4 v[64:65], off
	s_mov_b32 m0, s89
	v_lshl_add_u64 v[64:65], v[70:71], 0, s[6:7]
	global_load_lds_dwordx4 v78, s[66:67]
	s_mov_b32 m0, s90
	v_readlane_b32 s86, v254, 58
	global_load_lds_dwordx4 v[64:65], off
	s_mov_b32 m0, s91
	v_readlane_b32 s87, v254, 59
	global_load_lds_dwordx4 v84, s[66:67]
	ds_read_b128 v[64:67], v79
	ds_read_b128 v[68:71], v81 offset:16384
	ds_read_b128 v[88:91], v81 offset:20480
	s_waitcnt lgkmcnt(0)
	v_mfma_f32_32x32x16_bf16 v[48:63], v[64:67], v[68:71], v[48:63]
	v_mfma_f32_32x32x16_bf16 v[32:47], v[64:67], v[88:91], v[32:47]
	ds_read_b128 v[64:67], v79 offset:4096
	s_waitcnt lgkmcnt(0)
	v_mfma_f32_32x32x16_bf16 v[16:31], v[64:67], v[68:71], v[16:31]
	v_mfma_f32_32x32x16_bf16 v[0:15], v[64:67], v[88:91], v[0:15]
	ds_read_b128 v[64:67], v80
	ds_read_b128 v[68:71], v83 offset:16384
	ds_read_b128 v[88:91], v83 offset:20480
	s_waitcnt lgkmcnt(0)
	v_mfma_f32_32x32x16_bf16 v[48:63], v[64:67], v[68:71], v[48:63]
	v_mfma_f32_32x32x16_bf16 v[32:47], v[64:67], v[88:91], v[32:47]
	ds_read_b128 v[64:67], v80 offset:4096
	s_waitcnt lgkmcnt(0)
	v_mfma_f32_32x32x16_bf16 v[16:31], v[64:67], v[68:71], v[16:31]
	v_mfma_f32_32x32x16_bf16 v[0:15], v[64:67], v[88:91], v[0:15]
	ds_read_b128 v[64:67], v82
	ds_read_b128 v[68:71], v85 offset:16384
	ds_read_b128 v[88:91], v85 offset:20480
	s_waitcnt lgkmcnt(0)
	v_mfma_f32_32x32x16_bf16 v[48:63], v[64:67], v[68:71], v[48:63]
	v_mfma_f32_32x32x16_bf16 v[32:47], v[64:67], v[88:91], v[32:47]
	ds_read_b128 v[64:67], v82 offset:4096
	s_waitcnt lgkmcnt(0)
	v_mfma_f32_32x32x16_bf16 v[16:31], v[64:67], v[68:71], v[16:31]
	v_mfma_f32_32x32x16_bf16 v[0:15], v[64:67], v[88:91], v[0:15]
	ds_read_b128 v[64:67], v86
	ds_read_b128 v[68:71], v87 offset:16384
	ds_read_b128 v[88:91], v87 offset:20480
	s_waitcnt lgkmcnt(0)
	v_mfma_f32_32x32x16_bf16 v[48:63], v[64:67], v[68:71], v[48:63]
	v_mfma_f32_32x32x16_bf16 v[32:47], v[64:67], v[88:91], v[32:47]
	ds_read_b128 v[64:67], v86 offset:4096
	s_waitcnt vmcnt(0)
	s_waitcnt vmcnt(0) lgkmcnt(0)
	s_barrier
	v_mfma_f32_32x32x16_bf16 v[16:31], v[64:67], v[68:71], v[16:31]
	v_mfma_f32_32x32x16_bf16 v[0:15], v[64:67], v[88:91], v[0:15]
	ds_read_b128 v[64:67], v79 offset:32768
	ds_read_b128 v[68:71], v81 offset:49152
	ds_read_b128 v[88:91], v81 offset:53248
	s_waitcnt lgkmcnt(1)
	v_mfma_f32_32x32x16_bf16 v[48:63], v[64:67], v[68:71], v[48:63]
	s_waitcnt lgkmcnt(0)
	v_mfma_f32_32x32x16_bf16 v[32:47], v[64:67], v[88:91], v[32:47]
	ds_read_b128 v[64:67], v79 offset:36864
	s_waitcnt lgkmcnt(0)
	v_mfma_f32_32x32x16_bf16 v[16:31], v[64:67], v[68:71], v[16:31]
	v_mfma_f32_32x32x16_bf16 v[0:15], v[64:67], v[88:91], v[0:15]
	ds_read_b128 v[64:67], v80 offset:32768
	ds_read_b128 v[68:71], v83 offset:49152
	ds_read_b128 v[76:79], v83 offset:53248
	s_waitcnt lgkmcnt(1)
	v_mfma_f32_32x32x16_bf16 v[48:63], v[64:67], v[68:71], v[48:63]
	s_waitcnt lgkmcnt(0)
	v_mfma_f32_32x32x16_bf16 v[32:47], v[64:67], v[76:79], v[32:47]
	ds_read_b128 v[64:67], v80 offset:36864
	s_waitcnt lgkmcnt(0)
	v_mfma_f32_32x32x16_bf16 v[16:31], v[64:67], v[68:71], v[16:31]
	v_mfma_f32_32x32x16_bf16 v[0:15], v[64:67], v[76:79], v[0:15]
	ds_read_b128 v[64:67], v82 offset:32768
	ds_read_b128 v[68:71], v85 offset:49152
	ds_read_b128 v[76:79], v85 offset:53248
	s_waitcnt lgkmcnt(1)
	v_mfma_f32_32x32x16_bf16 v[48:63], v[64:67], v[68:71], v[48:63]
	s_waitcnt lgkmcnt(0)
	v_mfma_f32_32x32x16_bf16 v[32:47], v[64:67], v[76:79], v[32:47]
	ds_read_b128 v[64:67], v82 offset:36864
	s_waitcnt lgkmcnt(0)
	v_mfma_f32_32x32x16_bf16 v[16:31], v[64:67], v[68:71], v[16:31]
	ds_read_b128 v[68:71], v87 offset:53248
	ds_read_b128 v[80:83], v87 offset:49152
	ds_read_b128 v[88:91], v86 offset:36864
	ds_read_b128 v[84:87], v86 offset:32768
	s_waitcnt vmcnt(0)
	s_waitcnt lgkmcnt(0)
	s_barrier
; DI int ltid() { int t = threadIdx.x; asm volatile("" : "+v"(t)); return t; }
; DI float bf2f(unsigned short u) { return __uint_as_float(((unsigned)u) << 16); }
; template <class F>
; DI void epi_foreach(const f32x16 (&acc)[2][2], F f) {
;   const int lane = ltid() & 63, w = ltid() >> 6;
;   const int wm = w >> 1, wn = w & 1;
; #pragma unroll
;   for (int mb = 0; mb < 2; ++mb)
; #pragma unroll
;     for (int nb = 0; nb < 2; ++nb)
; #pragma unroll
;       for (int r = 0; r < 16; ++r) {
;         const int row = wm * 64 + mb * 32 + (r & 3) + 8 * (r >> 2) + 4 * (lane >> 5);
;         const int col = wn * 64 + nb * 32 + (lane & 31);
;         f(row, col, acc[mb][nb][r]);
;         if ((r & 7) == 7) __builtin_amdgcn_sched_barrier(0);
;       }
; }
; DI void phase_up(const Params& P, int layer, char* smem) {
;     ...
;     f32x16 acc[2][2];
;     gemm_core(smem, 16, Abase, (const char*)wup, aoff, boff, acc);
;     epi_foreach(acc, [&](int row, int col, float v) __attribute__((always_inline)) { Cs[row * 136 + col] = f2bf(v); });
;     __syncthreads();
;     {
;       const int col = tid & 63, rb = tid >> 6;
;       const int cv = nt * 64 + col, cg_ = DFF + nt * 64 + col;
;       const float w0v = cw[cv], w1v = cw[5632 + cv], w2v = cw[2 * 5632 + cv], bv = cb[cv];
;       const float w0g = cw[cg_], w1g = cw[5632 + cg_], w2g = cw[2 * 5632 + cg_], bgt = cb[cg_];
;       for (int r = 2 + rb; r < 128; r += 4) {
;         const int tb = tb0 + r;
;         if (tb < S_) {
;           const float val = bv + w0v * bf2f(Cs[(r - 2) * 136 + col]) + w1v * bf2f(Cs[(r - 1) * 136 + col]) + w2v * bf2f(Cs[r * 136 + col]);
;           const float gat = bgt + w0g * bf2f(Cs[(r - 2) * 136 + 64 + col]) + w1g * bf2f(Cs[(r - 1) * 136 + 64 + col]) + w2g * bf2f(Cs[r * 136 + 64 + col]);
;           const float a = gat / (1.f + __expf(-gat)) * val;
;           ACT[(size_t)(b * S_ + tb) * DFF + cv] = f2bf(a);
	v_add_lshl_u32 v118, s21, v74, 2
	v_or_b32_e32 v119, s21, v72
	v_lshlrev_b32_e32 v119, 2, v119
	v_add_u32_e32 v120, 0xb000, v118
	v_add_u32_e32 v121, 0x5800, v118
	v_add_u32_e32 v122, 0xb000, v119
	v_add_u32_e32 v123, 0x5800, v119
	global_load_dword v129, v118, s[12:13]
	global_load_dword v131, v120, s[10:11]
	global_load_dword v133, v121, s[10:11]
	global_load_dword v135, v118, s[10:11]
	global_load_dword v128, v119, s[12:13]
	global_load_dword v130, v122, s[10:11]
	global_load_dword v132, v123, s[10:11]
	global_load_dword v134, v119, s[10:11]
	v_mfma_f32_32x32x16_bf16 v[48:63], v[84:87], v[80:83], v[48:63]
	v_mfma_f32_32x32x16_bf16 v[0:15], v[64:67], v[76:79], v[0:15]
	v_mov_b32_e32 v64, v161
	v_mov_b32_e32 v65, v161
	v_lshrrev_b32_e32 v67, 3, v64
	v_and_b32_e32 v67, 4, v67
	v_lshrrev_b32_e32 v66, 1, v65
	v_and_b32_e32 v64, 31, v64
	v_and_or_b32 v64, v65, 64, v64
	v_and_or_b32 v65, v66, s3, v67
	v_mul_lo_u32 v65, v65, s97
	s_nop 1
	v_cvt_pk_bf16_f32 v48, v48, s0
	v_lshl_add_u32 v64, v64, 1, v65
	ds_write_b16 v64, v48
	v_cvt_pk_bf16_f32 v48, v49, s0
	ds_write_b16 v64, v48 offset:272
	v_cvt_pk_bf16_f32 v48, v50, s0
	ds_write_b16 v64, v48 offset:544
	v_cvt_pk_bf16_f32 v48, v51, s0
	ds_write_b16 v64, v48 offset:816
	v_cvt_pk_bf16_f32 v48, v52, s0
	ds_write_b16 v64, v48 offset:2176
	v_cvt_pk_bf16_f32 v48, v53, s0
	ds_write_b16 v64, v48 offset:2448
	v_cvt_pk_bf16_f32 v48, v54, s0
	ds_write_b16 v64, v48 offset:2720
	v_cvt_pk_bf16_f32 v48, v55, s0
	v_mfma_f32_32x32x16_bf16 v[32:47], v[84:87], v[68:71], v[32:47]
	ds_write_b16 v64, v48 offset:2992
	v_mfma_f32_32x32x16_bf16 v[16:31], v[88:91], v[80:83], v[16:31]
	v_mfma_f32_32x32x16_bf16 v[0:15], v[88:91], v[68:71], v[0:15]
	v_cvt_pk_bf16_f32 v48, v56, s0
	ds_write_b16 v64, v48 offset:4352
	v_cvt_pk_bf16_f32 v48, v57, s0
	ds_write_b16 v64, v48 offset:4624
	v_cvt_pk_bf16_f32 v48, v58, s0
	ds_write_b16 v64, v48 offset:4896
	v_cvt_pk_bf16_f32 v48, v59, s0
	ds_write_b16 v64, v48 offset:5168
	v_cvt_pk_bf16_f32 v48, v60, s0
	ds_write_b16 v64, v48 offset:6528
	v_cvt_pk_bf16_f32 v48, v61, s0
	ds_write_b16 v64, v48 offset:6800
	v_cvt_pk_bf16_f32 v48, v62, s0
	ds_write_b16 v64, v48 offset:7072
	v_cvt_pk_bf16_f32 v48, v63, s0
	ds_write_b16 v64, v48 offset:7344
	v_cvt_pk_bf16_f32 v32, v32, s0
	ds_write_b16 v64, v32 offset:64
	v_cvt_pk_bf16_f32 v32, v33, s0
	ds_write_b16 v64, v32 offset:336
	v_cvt_pk_bf16_f32 v32, v34, s0
	ds_write_b16 v64, v32 offset:608
	v_cvt_pk_bf16_f32 v32, v35, s0
	ds_write_b16 v64, v32 offset:880
	v_cvt_pk_bf16_f32 v32, v36, s0
	ds_write_b16 v64, v32 offset:2240
	v_cvt_pk_bf16_f32 v32, v37, s0
	ds_write_b16 v64, v32 offset:2512
	v_cvt_pk_bf16_f32 v32, v38, s0
	ds_write_b16 v64, v32 offset:2784
	v_cvt_pk_bf16_f32 v32, v39, s0
	ds_write_b16 v64, v32 offset:3056
	v_cvt_pk_bf16_f32 v32, v40, s0
	ds_write_b16 v64, v32 offset:4416
	v_cvt_pk_bf16_f32 v32, v41, s0
	ds_write_b16 v64, v32 offset:4688
	v_cvt_pk_bf16_f32 v32, v42, s0
	ds_write_b16 v64, v32 offset:4960
	v_cvt_pk_bf16_f32 v32, v43, s0
	ds_write_b16 v64, v32 offset:5232
	v_cvt_pk_bf16_f32 v32, v44, s0
	ds_write_b16 v64, v32 offset:6592
	v_cvt_pk_bf16_f32 v32, v45, s0
	ds_write_b16 v64, v32 offset:6864
	v_cvt_pk_bf16_f32 v32, v46, s0
	ds_write_b16 v64, v32 offset:7136
	v_cvt_pk_bf16_f32 v32, v47, s0
	ds_write_b16 v64, v32 offset:7408
	v_cvt_pk_bf16_f32 v16, v16, s0
	ds_write_b16 v64, v16 offset:8704
	v_cvt_pk_bf16_f32 v16, v17, s0
	ds_write_b16 v64, v16 offset:8976
	v_cvt_pk_bf16_f32 v16, v18, s0
	ds_write_b16 v64, v16 offset:9248
	v_cvt_pk_bf16_f32 v16, v19, s0
	ds_write_b16 v64, v16 offset:9520
	v_cvt_pk_bf16_f32 v16, v20, s0
	ds_write_b16 v64, v16 offset:10880
	v_cvt_pk_bf16_f32 v16, v21, s0
	ds_write_b16 v64, v16 offset:11152
	v_cvt_pk_bf16_f32 v16, v22, s0
	ds_write_b16 v64, v16 offset:11424
	v_cvt_pk_bf16_f32 v16, v23, s0
	ds_write_b16 v64, v16 offset:11696
	v_cvt_pk_bf16_f32 v16, v24, s0
	ds_write_b16 v64, v16 offset:13056
	v_cvt_pk_bf16_f32 v16, v25, s0
	ds_write_b16 v64, v16 offset:13328
	v_cvt_pk_bf16_f32 v16, v26, s0
	ds_write_b16 v64, v16 offset:13600
	v_cvt_pk_bf16_f32 v16, v27, s0
	ds_write_b16 v64, v16 offset:13872
	v_cvt_pk_bf16_f32 v16, v28, s0
	ds_write_b16 v64, v16 offset:15232
	v_cvt_pk_bf16_f32 v16, v29, s0
	ds_write_b16 v64, v16 offset:15504
	v_cvt_pk_bf16_f32 v16, v30, s0
	ds_write_b16 v64, v16 offset:15776
	v_cvt_pk_bf16_f32 v16, v31, s0
	ds_write_b16 v64, v16 offset:16048
	v_cvt_pk_bf16_f32 v0, v0, s0
	ds_write_b16 v64, v0 offset:8768
	v_cvt_pk_bf16_f32 v0, v1, s0
	ds_write_b16 v64, v0 offset:9040
	v_cvt_pk_bf16_f32 v0, v2, s0
	ds_write_b16 v64, v0 offset:9312
	v_cvt_pk_bf16_f32 v0, v3, s0
	ds_write_b16 v64, v0 offset:9584
	v_cvt_pk_bf16_f32 v0, v4, s0
	ds_write_b16 v64, v0 offset:10944
	v_cvt_pk_bf16_f32 v0, v5, s0
	ds_write_b16 v64, v0 offset:11216
	v_cvt_pk_bf16_f32 v0, v6, s0
	ds_write_b16 v64, v0 offset:11488
	v_cvt_pk_bf16_f32 v0, v7, s0
	ds_write_b16 v64, v0 offset:11760
	v_cvt_pk_bf16_f32 v0, v8, s0
	ds_write_b16 v64, v0 offset:13120
	v_cvt_pk_bf16_f32 v0, v9, s0
	ds_write_b16 v64, v0 offset:13392
	v_cvt_pk_bf16_f32 v0, v10, s0
	ds_write_b16 v64, v0 offset:13664
	v_cvt_pk_bf16_f32 v0, v11, s0
	ds_write_b16 v64, v0 offset:13936
	v_cvt_pk_bf16_f32 v0, v12, s0
	ds_write_b16 v64, v0 offset:15296
	v_cvt_pk_bf16_f32 v0, v13, s0
	ds_write_b16 v64, v0 offset:15568
	v_cvt_pk_bf16_f32 v0, v14, s0
	ds_write_b16 v64, v0 offset:15840
	v_cvt_pk_bf16_f32 v0, v15, s0
	ds_write_b16 v64, v0 offset:16112
	s_waitcnt lgkmcnt(0)
	s_barrier
	s_and_saveexec_b64 s[18:19], s[40:41]
	s_mov_b32 s3, 0xb000
	s_cbranch_execz .LBB0_24
	s_waitcnt vmcnt(0)
	v_add_u32_e32 v136, s21, v74
	v_lshlrev_b64 v[4:5], 2, v[136:137]
	v_lshl_add_u64 v[8:9], s[10:11], 0, v[4:5]
	v_or_b32_e32 v10, s21, v72
	v_lshl_add_u64 v[2:3], s[12:13], 0, v[4:5]
	v_add_co_u32_e32 v4, vcc, 0xb000, v8
	v_ashrrev_i32_e32 v11, 31, v10
	s_nop 0
	v_addc_co_u32_e32 v5, vcc, 0, v9, vcc
	v_lshl_add_u64 v[0:1], v[10:11], 1, s[86:87]
	v_add_co_u32_e32 v6, vcc, 0x5000, v8
	v_lshlrev_b64 v[10:11], 2, v[10:11]
	s_nop 0
	v_addc_co_u32_e32 v7, vcc, 0, v9, vcc
	v_lshl_add_u64 v[12:13], s[12:13], 0, v[10:11]
	v_lshl_add_u64 v[10:11], s[10:11], 0, v[10:11]
	v_mov_b32_e32 v3, v129
	s_mulk_i32 s20, 0x7e
	v_mov_b32_e32 v5, v131
	s_nop 0
	v_mov_b32_e32 v7, v133
	s_nop 0
	v_mov_b32_e32 v9, v135
	s_mul_i32 s21, s68, 0x7a
	v_mov_b32_e32 v2, v128
	v_add_co_u32_e32 v12, vcc, s3, v10
	s_sub_i32 s29, s20, s21
	s_nop 0
	v_addc_co_u32_e32 v13, vcc, 0, v11, vcc
	v_mov_b32_e32 v4, v130
	v_add_co_u32_e32 v12, vcc, 0x5000, v10
	s_mov_b64 s[20:21], 0
	s_nop 0
	v_addc_co_u32_e32 v13, vcc, 0, v11, vcc
	v_mov_b32_e32 v6, v132
	v_mov_b32_e32 v8, v134
	v_mov_b32_e32 v11, v73
	v_mov_b32_e32 v10, v75
	s_waitcnt vmcnt(0)
	s_branch .LBB0_28

; DI void transpose_v(const unsigned short* src, int ld, int col0, int hs, unsigned short* dst, char* smem) {
;     ...
;     for (int i = 0; i < 2; ++i) {
;       const int r = (tid >> 3) + 32 * i, ch = tid & 7;
;       u32x4 v = *(const u32x4*)(src + (size_t)(t0 + r) * ld + col0 + h * hs + ch * 8);
;       *(u32x4*)(ts + r * 72 + ch * 8) = v;
;     }
;     __syncthreads();
;     const int b = t0 / S_, s0 = t0 % S_;
; #pragma unroll
;     for (int i = 0; i < 2; ++i) {
;       const int dv = (tid >> 3) + 32 * i, c = tid & 7;
;       unsigned short e[8];
; #pragma unroll
;       for (int j = 0; j < 8; ++j) e[j] = ts[(8 * c + j) * 72 + dv];
;       u32x4 o;
;       o.x = e[0] | ((unsigned)e[1] << 16); o.y = e[2] | ((unsigned)e[3] << 16);
;       o.z = e[4] | ((unsigned)e[5] << 16); o.w = e[6] | ((unsigned)e[7] << 16);
;       *(u32x4*)(dst + ((size_t)((b * 8 + h) * 64 + dv)) * S_ + s0 + 8 * c) = o;
;     }
;     __syncthreads();
.LBB0_246:
	s_and_b32 s10, s0, 0xffffffc0
	s_and_b32 s11, s1, 7
	v_add_u32_e32 v8, s10, v4
	s_lshl_b32 s6, s11, 8
	v_ashrrev_i32_e32 v9, 31, v8
	v_lshl_add_u64 v[12:13], v[0:1], 0, s[6:7]
	v_lshlrev_b64 v[8:9], 11, v[8:9]
	v_lshl_add_u64 v[8:9], v[12:13], 0, v[8:9]
	global_load_dwordx4 v[8:11], v[8:9], off
	v_add_u32_e32 v24, s10, v5
	v_ashrrev_i32_e32 v25, 31, v24
	v_lshlrev_b64 v[24:25], 11, v[24:25]
	v_lshl_add_u64 v[24:25], v[12:13], 0, v[24:25]
	global_load_dwordx4 v[28:31], v[24:25], off
	s_ashr_i32 s2, s0, 31
	s_lshr_b32 s2, s2, 18
	s_add_i32 s2, s10, s2
	s_ashr_i32 s12, s2, 14
	s_and_b32 s2, s2, 0xffffc000
	s_lshl_b32 s11, s11, 6
	s_add_i32 s1, s1, s70
	s_add_i32 s0, s0, s3
	s_waitcnt vmcnt(1)
	ds_write_b128 v6, v[8:11]
	s_sub_i32 s10, s10, s2
	s_lshl_b32 s2, s12, 9
	s_or_b32 s2, s2, s11
	s_ashr_i32 s11, s10, 31
	v_lshl_add_u64 v[12:13], s[10:11], 1, v[2:3]
	s_cmpk_gt_i32 s1, 0xfff
	s_waitcnt vmcnt(0)
	ds_write_b128 v6, v[28:31] offset:4608
	s_waitcnt lgkmcnt(0)
	s_barrier
	ds_read_u16 v8, v7
	ds_read_u16 v14, v7 offset:144
	ds_read_u16 v9, v7 offset:288
	ds_read_u16 v15, v7 offset:432
	ds_read_u16 v10, v7 offset:576
	ds_read_u16 v16, v7 offset:720
	ds_read_u16 v11, v7 offset:864
	ds_read_u16 v17, v7 offset:1008
	s_waitcnt lgkmcnt(6)
	v_perm_b32 v8, v14, v8, s4
	v_add_u32_e32 v14, s2, v4
	s_waitcnt lgkmcnt(4)
	v_perm_b32 v9, v15, v9, s4
	v_ashrrev_i32_e32 v15, 31, v14
	v_lshlrev_b64 v[14:15], 15, v[14:15]
	s_waitcnt lgkmcnt(0)
	v_perm_b32 v11, v17, v11, s4
	v_perm_b32 v10, v16, v10, s4
	v_lshl_add_u64 v[14:15], v[12:13], 0, v[14:15]
	global_store_dwordx4 v[14:15], v[8:11], off
	ds_read_u16 v8, v7 offset:64
	ds_read_u16 v14, v7 offset:208
	ds_read_u16 v9, v7 offset:352
	ds_read_u16 v15, v7 offset:496
	ds_read_u16 v10, v7 offset:640
	ds_read_u16 v16, v7 offset:784
	ds_read_u16 v11, v7 offset:928
	ds_read_u16 v17, v7 offset:1072
	s_waitcnt lgkmcnt(6)
	v_perm_b32 v8, v14, v8, s4
	v_add_u32_e32 v14, s2, v5
	s_waitcnt lgkmcnt(4)
	v_perm_b32 v9, v15, v9, s4
	v_ashrrev_i32_e32 v15, 31, v14
	v_lshlrev_b64 v[14:15], 15, v[14:15]
	s_waitcnt lgkmcnt(0)
	v_perm_b32 v11, v17, v11, s4
	v_perm_b32 v10, v16, v10, s4
	v_lshl_add_u64 v[12:13], v[12:13], 0, v[14:15]
	global_store_dwordx4 v[12:13], v[8:11], off
	s_barrier
	s_cbranch_scc0 .LBB0_246
	v_writelane_b32 v253, s6, 17
	s_nop 1
	v_writelane_b32 v253, s7, 18

; DI void transpose_v(const unsigned short* src, int ld, int col0, int hs, unsigned short* dst, char* smem) {
;     ...
;     for (int i = 0; i < 2; ++i) {
;       const int r = (tid >> 3) + 32 * i, ch = tid & 7;
;       u32x4 v = *(const u32x4*)(src + (size_t)(t0 + r) * ld + col0 + h * hs + ch * 8);
;       *(u32x4*)(ts + r * 72 + ch * 8) = v;
;     }
;     __syncthreads();
;     const int b = t0 / S_, s0 = t0 % S_;
; #pragma unroll
;     for (int i = 0; i < 2; ++i) {
;       const int dv = (tid >> 3) + 32 * i, c = tid & 7;
;       unsigned short e[8];
; #pragma unroll
;       for (int j = 0; j < 8; ++j) e[j] = ts[(8 * c + j) * 72 + dv];
;       u32x4 o;
;       o.x = e[0] | ((unsigned)e[1] << 16); o.y = e[2] | ((unsigned)e[3] << 16);
;       o.z = e[4] | ((unsigned)e[5] << 16); o.w = e[6] | ((unsigned)e[7] << 16);
;       *(u32x4*)(dst + ((size_t)((b * 8 + h) * 64 + dv)) * S_ + s0 + 8 * c) = o;
;     }
;     __syncthreads();
.LBB0_430:
	s_and_b32 s14, s1, 0x1c0
	s_and_b32 s11, s0, 0xffffffc0
	s_lshl_b32 s6, s14, 1
	v_lshl_add_u64 v[12:13], v[0:1], 0, s[6:7]
	v_add_u32_e32 v8, s11, v4
	v_mad_i64_i32 v[8:9], s[12:13], v8, s33, v[12:13]
	global_load_dwordx4 v[8:11], v[8:9], off
	v_add_u32_e32 v24, s11, v5
	v_mad_i64_i32 v[24:25], s[12:13], v24, s33, v[12:13]
	global_load_dwordx4 v[28:31], v[24:25], off
	s_ashr_i32 s2, s0, 31
	s_lshr_b32 s2, s2, 18
	s_add_i32 s2, s11, s2
	s_add_i32 s10, s10, s70
	s_add_i32 s1, s1, s5
	s_add_i32 s0, s0, s4
	s_waitcnt vmcnt(1)
	ds_write_b128 v6, v[8:11]
	s_ashr_i32 s13, s2, 14
	s_and_b32 s2, s2, 0xffffc000
	s_sub_i32 s12, s11, s2
	s_lshl_b32 s2, s13, 9
	s_or_b32 s2, s2, s14
	s_ashr_i32 s13, s12, 31
	v_lshl_add_u64 v[12:13], s[12:13], 1, v[2:3]
	s_cmpk_gt_i32 s10, 0xfff
	s_waitcnt vmcnt(0)
	ds_write_b128 v6, v[28:31] offset:4608
	s_waitcnt lgkmcnt(0)
	s_barrier
	ds_read_u16 v8, v7
	ds_read_u16 v14, v7 offset:144
	ds_read_u16 v9, v7 offset:288
	ds_read_u16 v15, v7 offset:432
	ds_read_u16 v10, v7 offset:576
	ds_read_u16 v16, v7 offset:720
	ds_read_u16 v11, v7 offset:864
	ds_read_u16 v17, v7 offset:1008
	s_waitcnt lgkmcnt(6)
	v_perm_b32 v8, v14, v8, s3
	v_add_u32_e32 v14, s2, v4
	s_waitcnt lgkmcnt(4)
	v_perm_b32 v9, v15, v9, s3
	v_ashrrev_i32_e32 v15, 31, v14
	v_lshlrev_b64 v[14:15], 15, v[14:15]
	s_waitcnt lgkmcnt(0)
	v_perm_b32 v11, v17, v11, s3
	v_perm_b32 v10, v16, v10, s3
	v_lshl_add_u64 v[14:15], v[12:13], 0, v[14:15]
	global_store_dwordx4 v[14:15], v[8:11], off
	ds_read_u16 v8, v7 offset:64
	ds_read_u16 v14, v7 offset:208
	ds_read_u16 v9, v7 offset:352
	ds_read_u16 v15, v7 offset:496
	ds_read_u16 v10, v7 offset:640
	ds_read_u16 v16, v7 offset:784
	ds_read_u16 v11, v7 offset:928
	ds_read_u16 v17, v7 offset:1072
	s_waitcnt lgkmcnt(6)
	v_perm_b32 v8, v14, v8, s3
	v_add_u32_e32 v14, s2, v5
	s_waitcnt lgkmcnt(4)
	v_perm_b32 v9, v15, v9, s3
	v_ashrrev_i32_e32 v15, 31, v14
	v_lshlrev_b64 v[14:15], 15, v[14:15]
	s_waitcnt lgkmcnt(0)
	v_perm_b32 v11, v17, v11, s3
	v_perm_b32 v10, v16, v10, s3
	v_lshl_add_u64 v[12:13], v[12:13], 0, v[14:15]
	global_store_dwordx4 v[12:13], v[8:11], off
	s_barrier
	s_cbranch_scc0 .LBB0_430
